# C item: the 16 gate loads of the epilogue issued right after the xhat loads (spare VGPRs), counted waits raised by 16
# speedup vs baseline: 1.5530x; 1.0064x over previous
.LBB0_779:
	v_mov_b32_e32 v43, v0
	s_ashr_i32 s5, s3, 31
	v_ashrrev_i32_e32 v44, 7, v43
	s_waitcnt vmcnt(2)
	v_add_u32_e32 v164, s2, v44
	v_ashrrev_i32_e32 v165, 31, v164
	v_and_b32_e32 v168, 31, v43
	s_waitcnt vmcnt(0)
	v_lshlrev_b64 v[2:3], 15, v[164:165]
	v_bfe_u32 v169, v43, 5, 1
	v_lshl_add_u64 v[2:3], s[56:57], 0, v[2:3]
	v_lshlrev_b32_e32 v154, 8, v168
	v_lshl_add_u64 v[2:3], v[2:3], 0, v[154:155]
	v_lshlrev_b32_e32 v154, 4, v169
	v_lshl_add_u64 v[18:19], v[2:3], 0, v[154:155]
	v_add_co_u32_e32 v20, vcc, s14, v18
	v_ashrrev_i32_e32 v45, 2, v43
	s_nop 0
	v_addc_co_u32_e32 v21, vcc, 0, v19, vcc
	v_add_co_u32_e32 v22, vcc, s17, v18
	global_load_dwordx4 v[2:5], v[18:19], off
	global_load_dwordx4 v[6:9], v[20:21], off
	v_addc_co_u32_e32 v23, vcc, 0, v19, vcc
	v_add_co_u32_e32 v24, vcc, s30, v18
	global_load_dwordx4 v[10:13], v[22:23], off
	s_nop 0
	v_addc_co_u32_e32 v25, vcc, 0, v19, vcc
	global_load_dwordx4 v[14:17], v[24:25], off
	global_load_dwordx4 v[138:141], v[18:19], off offset:32
	global_load_dwordx4 v[142:145], v[20:21], off offset:32
	global_load_dwordx4 v[146:149], v[22:23], off offset:32
	global_load_dwordx4 v[150:153], v[24:25], off offset:32
	global_load_dwordx4 v[126:129], v[20:21], off offset:64
	global_load_dwordx4 v[130:133], v[22:23], off offset:64
	global_load_dwordx4 v[134:137], v[24:25], off offset:64
	global_load_dwordx4 v[114:117], v[20:21], off offset:96
	global_load_dwordx4 v[118:121], v[22:23], off offset:96
	global_load_dwordx4 v[122:125], v[24:25], off offset:96
	global_load_dwordx4 v[106:109], v[22:23], off offset:128
	global_load_dwordx4 v[110:113], v[24:25], off offset:128
	global_load_dwordx4 v[98:101], v[22:23], off offset:160
	global_load_dwordx4 v[102:105], v[24:25], off offset:160
	global_load_dwordx4 v[94:97], v[24:25], off offset:192
	global_load_dwordx4 v[90:93], v[24:25], off offset:224
	v_add_u32_e32 v18, s3, v45
	v_ashrrev_i32_e32 v19, 31, v18
	v_lshlrev_b32_e32 v20, 6, v43
	v_lshlrev_b64 v[18:19], 12, v[18:19]
	v_and_b32_e32 v46, 0xc0, v20
	v_lshl_add_u64 v[18:19], s[60:61], 0, v[18:19]
	v_lshlrev_b32_e32 v20, 1, v46
	v_mov_b32_e32 v21, v155
	v_lshl_add_u64 v[34:35], v[18:19], 0, v[20:21]
	global_load_dwordx4 v[18:21], v[34:35], off offset:3632
	global_load_dwordx4 v[22:25], v[34:35], off offset:3616
	global_load_dwordx4 v[26:29], v[34:35], off offset:3600
	global_load_dwordx4 v[30:33], v[34:35], off offset:3584
	global_load_dwordx4 v[36:39], v[34:35], off offset:3680
	global_load_dwordx4 v[202:205], v[34:35], off offset:3664
	global_load_dwordx4 v[48:51], v[34:35], off offset:3648
	global_load_dwordx4 v[206:209], v[34:35], off offset:3696
	v_and_b32_e32 v215, 31, v0
	v_add_u32_e32 v215, s3, v215
	v_lshlrev_b32_e32 v215, 12, v215
	v_and_b32_e32 v245, 0x1c0, v0
	v_add_u32_e32 v215, v215, v245
	v_bfe_u32 v245, v0, 5, 1
	v_lshl_add_u32 v215, v245, 3, v215
	global_load_dwordx2 v[216:217], v215, s[60:61] offset:3072
	global_load_dwordx2 v[218:219], v215, s[60:61] offset:3088
	global_load_dwordx2 v[220:221], v215, s[60:61] offset:3104
	global_load_dwordx2 v[222:223], v215, s[60:61] offset:3120
	s_add_u32 s98, s60, 0x20000
	s_addc_u32 s99, s61, 0
	global_load_dwordx2 v[224:225], v215, s[98:99] offset:3072
	global_load_dwordx2 v[226:227], v215, s[98:99] offset:3088
	global_load_dwordx2 v[228:229], v215, s[98:99] offset:3104
	global_load_dwordx2 v[230:231], v215, s[98:99] offset:3120
	s_add_u32 s100, s60, 0x40000
	s_addc_u32 s101, s61, 0
	global_load_dwordx2 v[232:233], v215, s[100:101] offset:3072
	global_load_dwordx2 v[234:235], v215, s[100:101] offset:3088
	global_load_dwordx2 v[236:237], v215, s[100:101] offset:3104
	global_load_dwordx2 v[238:239], v215, s[100:101] offset:3120
	s_add_u32 s98, s60, 0x60000
	s_addc_u32 s99, s61, 0
	global_load_dwordx2 v[240:241], v215, s[98:99] offset:3072
	global_load_dwordx2 v[246:247], v215, s[98:99] offset:3088
	global_load_dwordx2 v[252:253], v215, s[98:99] offset:3104
	global_load_dwordx2 v[254:255], v215, s[98:99] offset:3120
	v_lshrrev_b32_e32 v42, 5, v43
	s_add_i32 s4, s4, s46
	s_waitcnt vmcnt(23)
	v_lshlrev_b32_e32 v178, 16, v18
	s_waitcnt vmcnt(22)
	v_lshlrev_b32_e32 v186, 16, v22
	s_waitcnt vmcnt(21)
	v_lshlrev_b32_e32 v194, 16, v26
	s_waitcnt vmcnt(20)
	v_lshlrev_b32_e32 v200, 16, v30
	v_and_b32_e32 v199, 0xffff0000, v30
	v_add_f32_e32 v30, 0, v200
	v_lshlrev_b32_e32 v198, 16, v31
	v_add_f32_e32 v30, v30, v199
	v_and_b32_e32 v197, 0xffff0000, v31
	v_mul_f32_e32 v31, v199, v199
	v_add_f32_e32 v30, v30, v198
	v_lshlrev_b32_e32 v196, 16, v32
	v_fmac_f32_e32 v31, v200, v200
	v_add_f32_e32 v30, v30, v197
	v_and_b32_e32 v195, 0xffff0000, v32
	v_fmac_f32_e32 v31, v198, v198
	v_add_f32_e32 v30, v30, v196
	v_lshlrev_b32_e32 v193, 16, v33
	v_fmac_f32_e32 v31, v197, v197
	v_add_f32_e32 v30, v30, v195
	v_and_b32_e32 v191, 0xffff0000, v33
	v_fmac_f32_e32 v31, v196, v196
	v_add_f32_e32 v30, v30, v193
	v_fmac_f32_e32 v31, v195, v195
	v_add_f32_e32 v30, v30, v191
	v_fmac_f32_e32 v31, v193, v193
	v_and_b32_e32 v192, 0xffff0000, v26
	v_add_f32_e32 v26, v30, v194
	v_fmac_f32_e32 v31, v191, v191
	v_lshlrev_b32_e32 v190, 16, v27
	v_add_f32_e32 v26, v26, v192
	v_and_b32_e32 v189, 0xffff0000, v27
	v_fmac_f32_e32 v31, v194, v194
	v_add_f32_e32 v26, v26, v190
	v_lshlrev_b32_e32 v188, 16, v28
	v_fmac_f32_e32 v31, v192, v192
	v_add_f32_e32 v26, v26, v189
	v_and_b32_e32 v187, 0xffff0000, v28
	v_fmac_f32_e32 v31, v190, v190
	v_add_f32_e32 v26, v26, v188
	v_lshlrev_b32_e32 v184, 16, v29
	v_fmac_f32_e32 v31, v189, v189
	v_add_f32_e32 v26, v26, v187
	v_and_b32_e32 v182, 0xffff0000, v29
	v_fmac_f32_e32 v31, v188, v188
	v_add_f32_e32 v26, v26, v184
	v_fmac_f32_e32 v31, v187, v187
	v_add_f32_e32 v26, v26, v182
	v_fmac_f32_e32 v31, v184, v184
	v_and_b32_e32 v185, 0xffff0000, v22
	v_add_f32_e32 v22, v26, v186
	v_fmac_f32_e32 v31, v182, v182
	v_lshlrev_b32_e32 v183, 16, v23
	v_add_f32_e32 v22, v22, v185
	v_and_b32_e32 v179, 0xffff0000, v23
	v_fmac_f32_e32 v31, v186, v186
	v_add_f32_e32 v22, v22, v183
	v_lshlrev_b32_e32 v177, 16, v24
	v_fmac_f32_e32 v31, v185, v185
	v_add_f32_e32 v22, v22, v179
	v_and_b32_e32 v175, 0xffff0000, v24
	v_fmac_f32_e32 v31, v183, v183
	v_add_f32_e32 v22, v22, v177
	v_lshlrev_b32_e32 v173, 16, v25
	v_fmac_f32_e32 v31, v179, v179
	v_add_f32_e32 v22, v22, v175
	v_and_b32_e32 v171, 0xffff0000, v25
	v_fmac_f32_e32 v31, v177, v177
	v_add_f32_e32 v22, v22, v173
	v_fmac_f32_e32 v31, v175, v175
	v_add_f32_e32 v22, v22, v171
	v_fmac_f32_e32 v31, v173, v173
	v_and_b32_e32 v176, 0xffff0000, v18
	v_add_f32_e32 v18, v22, v178
	v_fmac_f32_e32 v31, v171, v171
	v_lshlrev_b32_e32 v174, 16, v19
	v_add_f32_e32 v18, v18, v176
	v_and_b32_e32 v172, 0xffff0000, v19
	v_fmac_f32_e32 v31, v178, v178
	v_add_f32_e32 v18, v18, v174
	v_lshlrev_b32_e32 v167, 16, v20
	v_fmac_f32_e32 v31, v176, v176
	v_add_f32_e32 v18, v18, v172
	v_and_b32_e32 v165, 0xffff0000, v20
	v_fmac_f32_e32 v31, v174, v174
	v_add_f32_e32 v18, v18, v167
	v_lshlrev_b32_e32 v64, 16, v21
	v_fmac_f32_e32 v31, v172, v172
	v_add_f32_e32 v18, v18, v165
	v_and_b32_e32 v62, 0xffff0000, v21
	v_fmac_f32_e32 v31, v167, v167
	v_add_f32_e32 v18, v18, v64
	v_fmac_f32_e32 v31, v165, v165
	v_add_f32_e32 v18, v18, v62
	s_waitcnt vmcnt(17)
	v_lshlrev_b32_e32 v170, 16, v48
	v_fmac_f32_e32 v31, v64, v64
	v_and_b32_e32 v166, 0xffff0000, v48
	v_add_f32_e32 v18, v18, v170
	v_fmac_f32_e32 v31, v62, v62
	v_lshlrev_b32_e32 v65, 16, v49
	v_add_f32_e32 v18, v18, v166
	v_and_b32_e32 v63, 0xffff0000, v49
	v_fmac_f32_e32 v31, v170, v170
	v_add_f32_e32 v18, v18, v65
	v_lshlrev_b32_e32 v60, 16, v50
	v_fmac_f32_e32 v31, v166, v166
	v_add_f32_e32 v18, v18, v63
	v_and_b32_e32 v59, 0xffff0000, v50
	v_fmac_f32_e32 v31, v65, v65
	v_add_f32_e32 v18, v18, v60
	v_lshlrev_b32_e32 v57, 16, v51
	v_fmac_f32_e32 v31, v63, v63
	v_add_f32_e32 v18, v18, v59
	v_and_b32_e32 v55, 0xffff0000, v51
	v_fmac_f32_e32 v31, v60, v60
	v_add_f32_e32 v18, v18, v57
	v_fmac_f32_e32 v31, v59, v59
	v_add_f32_e32 v18, v18, v55
	v_lshlrev_b32_e32 v61, 16, v202
	v_fmac_f32_e32 v31, v57, v57
	v_and_b32_e32 v58, 0xffff0000, v202
	v_add_f32_e32 v18, v18, v61
	v_fmac_f32_e32 v31, v55, v55
	v_lshlrev_b32_e32 v56, 16, v203
	v_add_f32_e32 v18, v18, v58
	v_and_b32_e32 v54, 0xffff0000, v203
	v_fmac_f32_e32 v31, v61, v61
	v_add_f32_e32 v18, v18, v56
	v_lshlrev_b32_e32 v53, 16, v204
	v_fmac_f32_e32 v31, v58, v58
	v_add_f32_e32 v18, v18, v54
	v_and_b32_e32 v51, 0xffff0000, v204
	v_fmac_f32_e32 v31, v56, v56
	v_add_f32_e32 v18, v18, v53
	v_lshlrev_b32_e32 v49, 16, v205
	v_fmac_f32_e32 v31, v54, v54
	v_add_f32_e32 v18, v18, v51
	v_and_b32_e32 v47, 0xffff0000, v205
	v_fmac_f32_e32 v31, v53, v53
	v_add_f32_e32 v18, v18, v49
	v_fmac_f32_e32 v31, v51, v51
	v_add_f32_e32 v18, v18, v47
	v_lshlrev_b32_e32 v52, 16, v36
	v_fmac_f32_e32 v31, v49, v49
	v_and_b32_e32 v50, 0xffff0000, v36
	v_add_f32_e32 v18, v18, v52
	v_fmac_f32_e32 v31, v47, v47
	v_lshlrev_b32_e32 v48, 16, v37
	v_add_f32_e32 v18, v18, v50
	v_fmac_f32_e32 v31, v52, v52
	v_add_f32_e32 v18, v18, v48
	v_and_b32_e32 v37, 0xffff0000, v37
	v_fmac_f32_e32 v31, v50, v50
	v_lshlrev_b32_e32 v34, 16, v38
	v_mov_b32_e32 v35, v37
	v_add_f32_e32 v20, v18, v37
	v_fmac_f32_e32 v31, v48, v48
	v_and_b32_e32 v24, 0xffff0000, v38
	v_pk_mul_f32 v[18:19], v[34:35], v[34:35]
	v_add_f32_e32 v20, v20, v34
	v_lshlrev_b32_e32 v25, 16, v39
	v_add_f32_e32 v19, v19, v31
	v_add_f32_e32 v20, v20, v24
	v_add_f32_e32 v21, v18, v19
	v_pk_mul_f32 v[18:19], v[24:25], v[24:25]
	v_add_f32_e32 v20, v20, v25
	v_and_b32_e32 v33, 0xffff0000, v39
	v_add_f32_e32 v18, v18, v21
	s_waitcnt vmcnt(16)
	v_lshlrev_b32_e32 v28, 16, v206
	v_mov_b32_e32 v29, v33
	v_add_f32_e32 v20, v20, v33
	v_add_f32_e32 v21, v19, v18
	v_and_b32_e32 v22, 0xffff0000, v206
	v_pk_mul_f32 v[18:19], v[28:29], v[28:29]
	v_add_f32_e32 v20, v20, v28
	v_lshlrev_b32_e32 v23, 16, v207
	v_add_f32_e32 v19, v19, v21
	v_add_f32_e32 v20, v20, v22
	v_add_f32_e32 v21, v18, v19
	v_pk_mul_f32 v[18:19], v[22:23], v[22:23]
	v_add_f32_e32 v29, v20, v23
	v_and_b32_e32 v31, 0xffff0000, v207
	v_add_f32_e32 v18, v18, v21
	v_lshlrev_b32_e32 v26, 16, v208
	v_mov_b32_e32 v27, v31
	v_add_f32_e32 v29, v29, v31
	v_and_b32_e32 v36, s0, v38
	v_add_f32_e32 v18, v19, v18
	v_and_b32_e32 v20, 0xffff0000, v208
	v_pk_mul_f32 v[38:39], v[26:27], v[26:27]
	v_add_f32_e32 v27, v29, v26
	v_lshlrev_b32_e32 v21, 16, v209
	v_add_f32_e32 v18, v39, v18
	v_add_f32_e32 v27, v27, v20
	v_and_b32_e32 v29, 64, v181
	v_add_f32_e32 v18, v38, v18
	v_pk_mul_f32 v[40:41], v[20:21], v[20:21]
	v_add_f32_e32 v39, v27, v21
	v_xor_b32_e32 v27, 1, v181
	v_add_u32_e32 v29, 64, v29
	v_and_b32_e32 v19, 0xffff0000, v209
	v_add_f32_e32 v18, v40, v18
	v_cmp_lt_i32_e32 vcc, v27, v29
	v_add_f32_e32 v18, v41, v18
	v_mul_f32_e32 v38, v19, v19
	v_cndmask_b32_e32 v27, v181, v27, vcc
	v_lshlrev_b32_e32 v27, 2, v27
	v_pk_add_f32 v[38:39], v[38:39], v[18:19]
	ds_bpermute_b32 v41, v27, v39
	ds_bpermute_b32 v40, v27, v38
	v_xor_b32_e32 v35, 2, v181
	v_cmp_lt_i32_e32 vcc, v35, v29
	v_and_b32_e32 v30, s0, v206
	v_mov_b32_e32 v32, v36
	v_cndmask_b32_e32 v29, v181, v35, vcc
	v_lshlrev_b32_e32 v29, 2, v29
	s_waitcnt lgkmcnt(0)
	v_pk_add_f32 v[38:39], v[38:39], v[40:41]
	ds_bpermute_b32 v41, v29, v39
	ds_bpermute_b32 v40, v29, v38
	s_waitcnt lgkmcnt(0)
	v_pk_add_f32 v[40:41], v[38:39], v[40:41]
	s_nop 0
	v_pk_mul_f32 v[38:39], v[40:41], s[22:23] op_sel_hi:[1,0]
	v_pk_fma_f32 v[36:37], v[40:41], s[22:23], v[36:37] op_sel_hi:[1,0,1] neg_lo:[1,0,0] neg_hi:[1,0,0]
	v_fma_f32 v18, -v39, v39, v38
	v_max_f32_e32 v18, 0, v18
	v_add_f32_e32 v18, 0x358637bd, v18
	v_cmp_gt_f32_e32 vcc, s33, v18
	v_mul_f32_e32 v27, 0x4b800000, v18
	v_sub_f32_e32 v29, v200, v39
	v_cndmask_b32_e32 v18, v18, v27, vcc
	v_rsq_f32_e32 v18, v18
	v_sub_f32_e32 v19, v19, v39
	v_mul_f32_e32 v27, 0x45800000, v18
	v_cndmask_b32_e32 v18, v18, v27, vcc
	v_mul_f32_e32 v29, v29, v18
	v_lshlrev_b32_e32 v27, 1, v45
	v_bfe_u32 v35, v29, 16, 1
	v_ashrrev_i32_e32 v45, 1, v43
	v_and_b32_e32 v27, 14, v27
	v_add3_u32 v29, v29, v35, s15
	v_lshl_add_u32 v35, v46, 8, 32
	v_and_b32_e32 v46, -16, v45
	v_add3_u32 v200, v35, v46, v27
	ds_write_b16_d16_hi v200, v29 offset:55296
	v_sub_f32_e32 v29, v199, v39
	v_mul_f32_e32 v29, v29, v18
	v_bfe_u32 v199, v29, 16, 1
	v_add3_u32 v29, v29, v199, s15
	v_bitop3_b32 v199, v45, 16, -16 bitop3:0x6c
	v_add3_u32 v201, v35, v199, v27
	ds_write_b16_d16_hi v201, v29 offset:55552
	v_sub_f32_e32 v29, v198, v39
	v_mul_f32_e32 v29, v29, v18
	v_bfe_u32 v198, v29, 16, 1
	v_add3_u32 v29, v29, v198, s15
	v_bitop3_b32 v198, v45, 32, -16 bitop3:0x6c
	v_add3_u32 v202, v35, v198, v27
	ds_write_b16_d16_hi v202, v29 offset:55808
	v_sub_f32_e32 v29, v197, v39
	v_mul_f32_e32 v29, v29, v18
	v_bfe_u32 v197, v29, 16, 1
	v_add3_u32 v29, v29, v197, s15
	v_bitop3_b32 v197, v45, 48, -16 bitop3:0x6c
	v_add3_u32 v203, v35, v197, v27
	ds_write_b16_d16_hi v203, v29 offset:56064
	v_sub_f32_e32 v29, v196, v39
	v_mul_f32_e32 v29, v29, v18
	v_bfe_u32 v196, v29, 16, 1
	v_add3_u32 v29, v29, v196, s15
	v_bitop3_b32 v196, v45, 64, -16 bitop3:0x6c
	v_add3_u32 v204, v35, v196, v27
	ds_write_b16_d16_hi v204, v29 offset:56320
	v_sub_f32_e32 v29, v195, v39
	v_mul_f32_e32 v29, v29, v18
	v_bfe_u32 v195, v29, 16, 1
	v_add3_u32 v29, v29, v195, s15
	v_bitop3_b32 v195, v45, s34, -16 bitop3:0x6c
	v_add3_u32 v205, v35, v195, v27
	ds_write_b16_d16_hi v205, v29 offset:56576
	v_sub_f32_e32 v29, v193, v39
	v_mul_f32_e32 v29, v29, v18
	v_bfe_u32 v193, v29, 16, 1
	v_add3_u32 v29, v29, v193, s15
	v_bitop3_b32 v193, v45, s31, -16 bitop3:0x6c
	v_add3_u32 v206, v35, v193, v27
	ds_write_b16_d16_hi v206, v29 offset:56832
	v_sub_f32_e32 v29, v191, v39
	v_mul_f32_e32 v29, v29, v18
	v_bfe_u32 v191, v29, 16, 1
	v_add3_u32 v29, v29, v191, s15
	v_bitop3_b32 v191, v45, s13, -16 bitop3:0x6c
	v_add3_u32 v207, v35, v191, v27
	ds_write_b16_d16_hi v207, v29 offset:57088
	v_sub_f32_e32 v29, v194, v39
	v_mul_f32_e32 v29, v29, v18
	v_bfe_u32 v194, v29, 16, 1
	v_add3_u32 v29, v29, v194, s15
	v_bitop3_b32 v194, v45, s12, -16 bitop3:0x6c
	v_add3_u32 v208, v35, v194, v27
	ds_write_b16_d16_hi v208, v29 offset:57344
	v_sub_f32_e32 v29, v192, v39
	v_mul_f32_e32 v29, v29, v18
	v_bfe_u32 v192, v29, 16, 1
	v_add3_u32 v29, v29, v192, s15
	v_bitop3_b32 v192, v45, s35, -16 bitop3:0x6c
	v_add3_u32 v209, v35, v192, v27
	ds_write_b16_d16_hi v209, v29 offset:57600
	v_sub_f32_e32 v29, v190, v39
	v_mul_f32_e32 v29, v29, v18
	v_bfe_u32 v190, v29, 16, 1
	v_add3_u32 v29, v29, v190, s15
	v_bitop3_b32 v190, v45, s36, -16 bitop3:0x6c
	v_add3_u32 v210, v35, v190, v27
	ds_write_b16_d16_hi v210, v29 offset:57856
	v_sub_f32_e32 v29, v189, v39
	v_mul_f32_e32 v29, v29, v18
	v_bfe_u32 v189, v29, 16, 1
	v_add3_u32 v29, v29, v189, s15
	v_bitop3_b32 v189, v45, s37, -16 bitop3:0x6c
	v_add3_u32 v211, v35, v189, v27
	ds_write_b16_d16_hi v211, v29 offset:58112
	v_sub_f32_e32 v29, v188, v39
	v_mul_f32_e32 v29, v29, v18
	v_bfe_u32 v188, v29, 16, 1
	v_add3_u32 v29, v29, v188, s15
	v_bitop3_b32 v188, v45, s16, -16 bitop3:0x6c
	v_add3_u32 v212, v35, v188, v27
	ds_write_b16_d16_hi v212, v29 offset:58368
	v_sub_f32_e32 v29, v187, v39
	v_mul_f32_e32 v29, v29, v18
	v_bfe_u32 v187, v29, 16, 1
	v_add3_u32 v29, v29, v187, s15
	v_bitop3_b32 v187, v45, s42, -16 bitop3:0x6c
	v_add3_u32 v213, v35, v187, v27
	ds_write_b16_d16_hi v213, v29 offset:58624
	v_sub_f32_e32 v29, v184, v39
	v_mul_f32_e32 v29, v29, v18
	v_bfe_u32 v184, v29, 16, 1
	v_add3_u32 v29, v29, v184, s15
	v_bitop3_b32 v184, v45, s43, -16 bitop3:0x6c
	v_add3_u32 v214, v35, v184, v27
	ds_write_b16_d16_hi v214, v29 offset:58880
	v_sub_f32_e32 v29, v182, v39
	v_mul_f32_e32 v29, v29, v18
	v_bfe_u32 v182, v29, 16, 1
	v_bitop3_b32 v45, v45, s94, -16 bitop3:0x6c
	v_add_u32_e32 v38, 0xd800, v35
	v_add3_u32 v29, v29, v182, s15
	v_add3_u32 v35, v35, v45, v27
	ds_write_b16_d16_hi v35, v29 offset:59136
	v_sub_f32_e32 v29, v186, v39
	v_mul_f32_e32 v29, v29, v18
	v_bfe_u32 v182, v29, 16, 1
	v_add3_u32 v29, v29, v182, s15
	ds_write_b16_d16_hi v200, v29 offset:59392
	v_sub_f32_e32 v29, v185, v39
	v_mul_f32_e32 v29, v29, v18
	v_bfe_u32 v182, v29, 16, 1
	v_add3_u32 v29, v29, v182, s15
	ds_write_b16_d16_hi v201, v29 offset:59648
	v_sub_f32_e32 v29, v183, v39
	v_mul_f32_e32 v29, v29, v18
	v_bfe_u32 v182, v29, 16, 1
	v_add3_u32 v29, v29, v182, s15
	ds_write_b16_d16_hi v202, v29 offset:59904
	v_sub_f32_e32 v29, v179, v39
	v_mul_f32_e32 v29, v29, v18
	v_bfe_u32 v179, v29, 16, 1
	v_add3_u32 v29, v29, v179, s15
	ds_write_b16_d16_hi v203, v29 offset:60160
	v_sub_f32_e32 v29, v177, v39
	v_mul_f32_e32 v29, v29, v18
	v_bfe_u32 v177, v29, 16, 1
	v_add3_u32 v29, v29, v177, s15
	ds_write_b16_d16_hi v204, v29 offset:60416
	v_sub_f32_e32 v29, v175, v39
	v_mul_f32_e32 v29, v29, v18
	v_bfe_u32 v175, v29, 16, 1
	v_add3_u32 v29, v29, v175, s15
	ds_write_b16_d16_hi v205, v29 offset:60672
	v_sub_f32_e32 v29, v173, v39
	v_mul_f32_e32 v29, v29, v18
	v_bfe_u32 v173, v29, 16, 1
	v_add3_u32 v29, v29, v173, s15
	ds_write_b16_d16_hi v206, v29 offset:60928
	v_sub_f32_e32 v29, v171, v39
	v_mul_f32_e32 v29, v29, v18
	v_bfe_u32 v171, v29, 16, 1
	v_add3_u32 v29, v29, v171, s15
	ds_write_b16_d16_hi v207, v29 offset:61184
	v_sub_f32_e32 v29, v178, v39
	v_mul_f32_e32 v29, v29, v18
	v_bfe_u32 v171, v29, 16, 1
	v_add3_u32 v29, v29, v171, s15
	ds_write_b16_d16_hi v208, v29 offset:61440
	v_sub_f32_e32 v29, v176, v39
	v_mul_f32_e32 v29, v29, v18
	v_bfe_u32 v171, v29, 16, 1
	v_add3_u32 v29, v29, v171, s15
	ds_write_b16_d16_hi v209, v29 offset:61696
	v_sub_f32_e32 v29, v174, v39
	v_mul_f32_e32 v29, v29, v18
	v_bfe_u32 v171, v29, 16, 1
	v_add3_u32 v29, v29, v171, s15
	ds_write_b16_d16_hi v210, v29 offset:61952
	v_sub_f32_e32 v29, v172, v39
	v_mul_f32_e32 v29, v29, v18
	v_bfe_u32 v171, v29, 16, 1
	v_add3_u32 v29, v29, v171, s15
	ds_write_b16_d16_hi v211, v29 offset:62208
	v_sub_f32_e32 v29, v167, v39
	v_mul_f32_e32 v29, v29, v18
	v_bfe_u32 v167, v29, 16, 1
	v_add3_u32 v29, v29, v167, s15
	ds_write_b16_d16_hi v212, v29 offset:62464
	v_sub_f32_e32 v29, v165, v39
	v_mul_f32_e32 v29, v29, v18
	v_bfe_u32 v165, v29, 16, 1
	v_add3_u32 v29, v29, v165, s15
	ds_write_b16_d16_hi v213, v29 offset:62720
	v_sub_f32_e32 v29, v64, v39
	v_mul_f32_e32 v29, v29, v18
	v_bfe_u32 v64, v29, 16, 1
	v_add3_u32 v29, v29, v64, s15
	ds_write_b16_d16_hi v214, v29 offset:62976
	v_sub_f32_e32 v29, v62, v39
	v_mul_f32_e32 v29, v29, v18
	v_bfe_u32 v62, v29, 16, 1
	v_add3_u32 v29, v29, v62, s15
	ds_write_b16_d16_hi v35, v29 offset:63232
	v_sub_f32_e32 v29, v170, v39
	v_mul_f32_e32 v29, v29, v18
	v_bfe_u32 v35, v29, 16, 1
	v_add3_u32 v29, v29, v35, s15
	ds_write_b16_d16_hi v200, v29 offset:63488
	v_sub_f32_e32 v29, v166, v39
	v_mul_f32_e32 v29, v29, v18
	v_bfe_u32 v35, v29, 16, 1
	v_add3_u32 v29, v29, v35, s15
	ds_write_b16_d16_hi v201, v29 offset:63744
	v_sub_f32_e32 v29, v65, v39
	v_mul_f32_e32 v29, v29, v18
	v_bfe_u32 v35, v29, 16, 1
	v_add3_u32 v29, v29, v35, s15
	ds_write_b16_d16_hi v202, v29 offset:64000
	v_sub_f32_e32 v29, v63, v39
	v_mul_f32_e32 v29, v29, v18
	v_bfe_u32 v35, v29, 16, 1
	v_add3_u32 v29, v29, v35, s15
	ds_write_b16_d16_hi v203, v29 offset:64256
	v_sub_f32_e32 v29, v60, v39
	v_mul_f32_e32 v29, v29, v18
	v_bfe_u32 v35, v29, 16, 1
	v_add3_u32 v29, v29, v35, s15
	ds_write_b16_d16_hi v204, v29 offset:64512
	v_sub_f32_e32 v29, v59, v39
	v_mul_f32_e32 v29, v29, v18
	v_bfe_u32 v35, v29, 16, 1
	v_add3_u32 v29, v29, v35, s15
	ds_write_b16_d16_hi v205, v29 offset:64768
	v_sub_f32_e32 v29, v57, v39
	v_mul_f32_e32 v29, v29, v18
	v_bfe_u32 v35, v29, 16, 1
	v_add3_u32 v29, v29, v35, s15
	ds_write_b16_d16_hi v206, v29 offset:65024
	v_sub_f32_e32 v29, v55, v39
	v_mul_f32_e32 v29, v29, v18
	v_bfe_u32 v35, v29, 16, 1
	v_add3_u32 v29, v29, v35, s15
	ds_write_b16_d16_hi v207, v29 offset:65280
	v_sub_f32_e32 v29, v61, v39
	v_mul_f32_e32 v29, v29, v18
	v_bfe_u32 v35, v29, 16, 1
	v_add3_u32 v29, v29, v35, s15
	v_add3_u32 v35, v38, v194, v27
	ds_write_b16_d16_hi v35, v29 offset:10240
	v_sub_f32_e32 v29, v58, v39
	v_mul_f32_e32 v29, v29, v18
	v_bfe_u32 v55, v29, 16, 1
	v_add3_u32 v29, v29, v55, s15
	v_add3_u32 v55, v38, v192, v27
	ds_write_b16_d16_hi v55, v29 offset:10496
	v_sub_f32_e32 v29, v56, v39
	v_mul_f32_e32 v29, v29, v18
	v_bfe_u32 v56, v29, 16, 1
	v_add3_u32 v29, v29, v56, s15
	v_add3_u32 v56, v38, v190, v27
	ds_write_b16_d16_hi v56, v29 offset:10752
	v_sub_f32_e32 v29, v54, v39
	v_mul_f32_e32 v29, v29, v18
	v_bfe_u32 v54, v29, 16, 1
	v_add3_u32 v29, v29, v54, s15
	v_add3_u32 v54, v38, v189, v27
	ds_write_b16_d16_hi v54, v29 offset:11008
	v_sub_f32_e32 v29, v53, v39
	v_mul_f32_e32 v29, v29, v18
	v_bfe_u32 v53, v29, 16, 1
	v_add3_u32 v29, v29, v53, s15
	v_add3_u32 v53, v38, v188, v27
	ds_write_b16_d16_hi v53, v29 offset:11264
	v_sub_f32_e32 v29, v51, v39
	v_mul_f32_e32 v29, v29, v18
	v_bfe_u32 v51, v29, 16, 1
	v_add3_u32 v29, v29, v51, s15
	v_add3_u32 v51, v38, v187, v27
	ds_write_b16_d16_hi v51, v29 offset:11520
	v_sub_f32_e32 v29, v49, v39
	v_mul_f32_e32 v29, v29, v18
	v_bfe_u32 v49, v29, 16, 1
	v_add3_u32 v29, v29, v49, s15
	v_add3_u32 v49, v38, v184, v27
	ds_write_b16_d16_hi v49, v29 offset:11776
	v_sub_f32_e32 v29, v47, v39
	v_mul_f32_e32 v29, v29, v18
	v_bfe_u32 v47, v29, 16, 1
	v_add3_u32 v29, v29, v47, s15
	v_add3_u32 v45, v38, v45, v27
	ds_write_b16_d16_hi v45, v29 offset:12032
	v_sub_f32_e32 v29, v52, v39
	v_mul_f32_e32 v29, v29, v18
	v_bfe_u32 v47, v29, 16, 1
	v_add3_u32 v29, v29, v47, s15
	v_add3_u32 v46, v38, v46, v27
	ds_write_b16_d16_hi v46, v29 offset:12288
	v_sub_f32_e32 v29, v50, v39
	v_mul_f32_e32 v29, v29, v18
	v_bfe_u32 v46, v29, 16, 1
	v_add3_u32 v29, v29, v46, s15
	v_add3_u32 v46, v38, v199, v27
	ds_write_b16_d16_hi v46, v29 offset:12544
	v_sub_f32_e32 v29, v48, v39
	v_mul_f32_e32 v29, v29, v18
	v_bfe_u32 v46, v29, 16, 1
	v_add3_u32 v29, v29, v46, s15
	v_add3_u32 v46, v38, v198, v27
	ds_write_b16_d16_hi v46, v29 offset:12800
	v_mul_f32_e32 v29, v37, v18
	v_bfe_u32 v36, v29, 16, 1
	v_add3_u32 v29, v29, v36, s15
	v_add3_u32 v36, v38, v197, v27
	ds_write_b16_d16_hi v36, v29 offset:13056
	v_sub_f32_e32 v29, v34, v39
	v_mul_f32_e32 v29, v29, v18
	v_bfe_u32 v34, v29, 16, 1
	v_add3_u32 v29, v29, v34, s15
	v_add3_u32 v34, v38, v196, v27
	ds_write_b16_d16_hi v34, v29 offset:13312
	v_sub_f32_e32 v29, v24, v39
	v_pk_fma_f32 v[24:25], v[40:41], s[22:23], v[24:25] op_sel_hi:[1,0,1] neg_lo:[1,0,0] neg_hi:[1,0,0]
	v_mul_f32_e32 v29, v29, v18
	v_mul_f32_e32 v24, v25, v18
	v_bfe_u32 v34, v29, 16, 1
	v_bfe_u32 v25, v24, 16, 1
	v_add3_u32 v29, v29, v34, s15
	v_add3_u32 v34, v38, v195, v27
	v_add3_u32 v24, v24, v25, s15
	v_add3_u32 v25, v38, v193, v27
	ds_write_b16_d16_hi v34, v29 offset:13568
	ds_write_b16_d16_hi v25, v24 offset:13824
	v_pk_fma_f32 v[24:25], v[40:41], s[22:23], v[32:33] op_sel_hi:[1,0,1] neg_lo:[1,0,0] neg_hi:[1,0,0]
	v_and_b32_e32 v167, 15, v43
	v_mul_f32_e32 v24, v25, v18
	v_bfe_u32 v25, v24, 16, 1
	v_add3_u32 v24, v24, v25, s15
	v_add3_u32 v25, v38, v191, v27
	ds_write_b16_d16_hi v25, v24 offset:14080
	v_sub_f32_e32 v24, v28, v39
	v_mul_f32_e32 v24, v24, v18
	v_bfe_u32 v25, v24, 16, 1
	v_add3_u32 v24, v24, v25, s15
	ds_write_b16_d16_hi v35, v24 offset:14336
	v_sub_f32_e32 v24, v22, v39
	v_pk_fma_f32 v[22:23], v[40:41], s[22:23], v[22:23] op_sel_hi:[1,0,1] neg_lo:[1,0,0] neg_hi:[1,0,0]
	v_mul_f32_e32 v24, v24, v18
	v_mul_f32_e32 v22, v23, v18
	v_bfe_u32 v25, v24, 16, 1
	v_bfe_u32 v23, v22, 16, 1
	v_add3_u32 v24, v24, v25, s15
	v_add3_u32 v22, v22, v23, s15
	ds_write_b16_d16_hi v55, v24 offset:14592
	ds_write_b16_d16_hi v56, v22 offset:14848
	v_pk_fma_f32 v[22:23], v[40:41], s[22:23], v[30:31] op_sel_hi:[1,0,1] neg_lo:[1,0,0] neg_hi:[1,0,0]
	s_nop 0
	v_mul_f32_e32 v22, v23, v18
	v_bfe_u32 v23, v22, 16, 1
	v_add3_u32 v22, v22, v23, s15
	ds_write_b16_d16_hi v54, v22 offset:15104
	v_sub_f32_e32 v22, v26, v39
	v_mul_f32_e32 v22, v22, v18
	v_bfe_u32 v23, v22, 16, 1
	v_add3_u32 v22, v22, v23, s15
	ds_write_b16_d16_hi v53, v22 offset:15360
	v_sub_f32_e32 v22, v20, v39
	v_pk_fma_f32 v[20:21], v[40:41], s[22:23], v[20:21] op_sel_hi:[1,0,1] neg_lo:[1,0,0] neg_hi:[1,0,0]
	v_mul_f32_e32 v22, v22, v18
	v_mul_f32_e32 v20, v21, v18
	v_mul_f32_e32 v18, v19, v18
	v_bfe_u32 v23, v22, 16, 1
	v_bfe_u32 v21, v20, 16, 1
	v_bfe_u32 v19, v18, 16, 1
	v_add3_u32 v22, v22, v23, s15
	v_add3_u32 v20, v20, v21, s15
	v_add3_u32 v18, v18, v19, s15
	ds_write_b16_d16_hi v51, v22 offset:15616
	ds_write_b16_d16_hi v49, v20 offset:15872
	ds_write_b16_d16_hi v45, v18 offset:16128
	v_lshrrev_b32_e32 v18, 1, v43
	v_and_b32_e32 v18, 32, v18
	v_lshl_or_b32 v166, v44, 6, v18
	v_or_b32_e32 v18, v166, v168
	v_lshl_add_u32 v165, v18, 8, 32
	v_bitop3_b32 v18, v42, v167, 1 bitop3:0x6c
	v_lshl_add_u32 v18, v18, 4, v165
	s_waitcnt lgkmcnt(0)
	s_barrier
	ds_read_b128 v[170:173], v18 offset:55296
	s_waitcnt lgkmcnt(0)
	v_mfma_f32_32x32x16_bf16 v[50:65], v[170:173], v[2:5], 0
	v_mfma_f32_32x32x16_bf16 v[34:49], v[170:173], v[6:9], 0
	v_mfma_f32_32x32x16_bf16 v[18:33], v[170:173], v[10:13], 0
	v_mfma_f32_32x32x16_bf16 v[2:17], v[170:173], v[14:17], 0
	v_bitop3_b32 v170, v169, v167, 2 bitop3:0x36
	v_lshl_add_u32 v170, v170, 4, v165
	ds_read_b128 v[170:173], v170 offset:55296
	s_waitcnt lgkmcnt(0)
	v_mfma_f32_32x32x16_bf16 v[50:65], v[170:173], v[138:141], v[50:65]
	v_bitop3_b32 v138, v169, v167, 4 bitop3:0x36
	v_lshl_add_u32 v138, v138, 4, v165
	ds_read_b128 v[138:141], v138 offset:55296
	v_mfma_f32_32x32x16_bf16 v[34:49], v[170:173], v[142:145], v[34:49]
	v_mfma_f32_32x32x16_bf16 v[18:33], v[170:173], v[146:149], v[18:33]
	s_waitcnt lgkmcnt(0)
	v_mfma_f32_32x32x16_bf16 v[34:49], v[138:141], v[126:129], v[34:49]
	v_bitop3_b32 v126, v169, v167, 6 bitop3:0x36
	v_lshl_add_u32 v126, v126, 4, v165
	ds_read_b128 v[126:129], v126 offset:55296
	v_mfma_f32_32x32x16_bf16 v[2:17], v[170:173], v[150:153], v[2:17]
	v_mfma_f32_32x32x16_bf16 v[18:33], v[138:141], v[130:133], v[18:33]
	s_waitcnt lgkmcnt(0)
	v_mfma_f32_32x32x16_bf16 v[34:49], v[126:129], v[114:117], v[34:49]
	v_bitop3_b32 v114, v169, v167, 8 bitop3:0x36
	v_lshl_add_u32 v114, v114, 4, v165
	ds_read_b128 v[114:117], v114 offset:55296
	v_mfma_f32_32x32x16_bf16 v[2:17], v[138:141], v[134:137], v[2:17]
	v_mfma_f32_32x32x16_bf16 v[18:33], v[126:129], v[118:121], v[18:33]
	v_mfma_f32_32x32x16_bf16 v[2:17], v[126:129], v[122:125], v[2:17]
	v_lshlrev_b32_e32 v128, 7, v164
	v_or_b32_e32 v126, v128, v168
	v_ashrrev_i32_e32 v127, 31, v126
	v_lshlrev_b64 v[130:131], 2, v[126:127]
	v_lshl_or_b32 v122, v169, 2, v166
	v_or_b32_e32 v124, s3, v168
	v_mov_b32_e32 v125, s5
	s_waitcnt lgkmcnt(0)
	v_mfma_f32_32x32x16_bf16 v[18:33], v[114:117], v[106:109], v[18:33]
	v_bitop3_b32 v106, v169, v167, 10 bitop3:0x36
	v_lshl_add_u32 v106, v106, 4, v165
	ds_read_b128 v[106:109], v106 offset:55296
	v_lshl_add_u64 v[132:133], s[6:7], 0, v[130:131]
	v_lshl_add_u64 v[130:131], s[92:93], 0, v[130:131]
	v_ashrrev_i32_e32 v123, 31, v122
	v_lshlrev_b64 v[122:123], 1, v[122:123]
	v_mfma_f32_32x32x16_bf16 v[2:17], v[114:117], v[110:113], v[2:17]
	s_add_i32 s3, s3, s18
	s_cmpk_gt_i32 s4, 0x7f
	s_waitcnt lgkmcnt(0)
	v_mfma_f32_32x32x16_bf16 v[18:33], v[106:109], v[98:101], v[18:33]
	v_bitop3_b32 v98, v169, v167, 12 bitop3:0x36
	v_lshl_add_u32 v98, v98, 4, v165
	ds_read_b128 v[98:101], v98 offset:55296
	v_mfma_f32_32x32x16_bf16 v[2:17], v[106:109], v[102:105], v[2:17]
	s_waitcnt lgkmcnt(0)
	v_mfma_f32_32x32x16_bf16 v[2:17], v[98:101], v[94:97], v[2:17]
	v_bitop3_b32 v94, v169, v167, 14 bitop3:0x36
	v_lshl_add_u32 v94, v94, 4, v165
	ds_read_b128 v[94:97], v94 offset:55296
	v_ashrrev_i32_e32 v167, 31, v166
	s_waitcnt lgkmcnt(0)
	v_mfma_f32_32x32x16_bf16 v[2:17], v[94:97], v[90:93], v[2:17]
	v_lshlrev_b64 v[90:91], 2, v[166:167]
	v_lshl_add_u64 v[92:93], s[10:11], 0, v[90:91]
	v_lshl_add_u64 v[90:91], s[40:41], 0, v[90:91]
	v_lshl_add_u64 v[92:93], v[92:93], 0, v[154:155]
	v_lshl_add_u64 v[94:95], v[90:91], 0, v[154:155]
	global_load_dwordx4 v[114:117], v[92:93], off
	global_load_dwordx4 v[118:121], v[94:95], off
	global_load_dwordx4 v[106:109], v[92:93], off offset:32
	global_load_dwordx4 v[110:113], v[94:95], off offset:32
	global_load_dwordx4 v[98:101], v[92:93], off offset:64
	global_load_dwordx4 v[102:105], v[94:95], off offset:64
	s_nop 0
	global_load_dwordx4 v[90:93], v[92:93], off offset:96
	s_nop 0
	global_load_dwordx4 v[94:97], v[94:95], off offset:96
	s_nop 0
	global_load_dword v186, v[132:133], off
	global_load_dword v187, v[132:133], off offset:128
	global_load_dword v188, v[132:133], off offset:256
	global_load_dword v189, v[132:133], off offset:384
	global_load_dword v190, v[130:131], off
	global_load_dword v191, v[130:131], off offset:128
	global_load_dword v192, v[130:131], off offset:256
	global_load_dword v193, v[130:131], off offset:384
	v_lshlrev_b64 v[176:177], 11, v[124:125]
	v_lshl_add_u64 v[176:177], s[62:63], 0, v[176:177]
	v_lshl_add_u64 v[176:177], v[176:177], 0, v[122:123]
	v_add_co_u32_e32 v178, vcc, 0x10000, v176
	s_nop 1
	v_addc_co_u32_e32 v179, vcc, 0, v177, vcc
	v_add_co_u32_e32 v182, vcc, 0x20000, v176
	s_nop 1
	v_addc_co_u32_e32 v183, vcc, 0, v177, vcc
	v_add_co_u32_e32 v184, vcc, 0x30000, v176
	s_nop 1
	v_addc_co_u32_e32 v185, vcc, 0, v177, vcc
	s_waitcnt vmcnt(0)
	v_mul_f32_e32 v194, v118, v186
	v_fmac_f32_e32 v194, v50, v114
	v_add_f32_e32 v50, v190, v194
	v_lshlrev_b32_e32 v195, 16, v216
	v_mul_f32_e32 v50, v50, v195
	v_mul_f32_e32 v194, v119, v186
	v_fmac_f32_e32 v194, v51, v115
	v_add_f32_e32 v51, v190, v194
	v_and_b32_e32 v195, 0xffff0000, v216
	v_mul_f32_e32 v51, v51, v195
	v_mul_f32_e32 v194, v120, v186
	v_fmac_f32_e32 v194, v52, v116
	v_add_f32_e32 v52, v190, v194
	v_lshlrev_b32_e32 v195, 16, v217
	v_mul_f32_e32 v52, v52, v195
	v_mul_f32_e32 v194, v121, v186
	v_fmac_f32_e32 v194, v53, v117
	v_add_f32_e32 v53, v190, v194
	v_and_b32_e32 v195, 0xffff0000, v217
	v_mul_f32_e32 v53, v53, v195
	v_cvt_pk_bf16_f32 v50, v50, v51
	v_cvt_pk_bf16_f32 v51, v52, v53
	global_store_dwordx2 v[176:177], v[50:51], off offset:1536
	v_mul_f32_e32 v194, v110, v186
	v_fmac_f32_e32 v194, v54, v106
	v_add_f32_e32 v54, v190, v194
	v_lshlrev_b32_e32 v195, 16, v218
	v_mul_f32_e32 v54, v54, v195
	v_mul_f32_e32 v194, v111, v186
	v_fmac_f32_e32 v194, v55, v107
	v_add_f32_e32 v55, v190, v194
	v_and_b32_e32 v195, 0xffff0000, v218
	v_mul_f32_e32 v55, v55, v195
	v_mul_f32_e32 v194, v112, v186
	v_fmac_f32_e32 v194, v56, v108
	v_add_f32_e32 v56, v190, v194
	v_lshlrev_b32_e32 v195, 16, v219
	v_mul_f32_e32 v56, v56, v195
	v_mul_f32_e32 v194, v113, v186
	v_fmac_f32_e32 v194, v57, v109
	v_add_f32_e32 v57, v190, v194
	v_and_b32_e32 v195, 0xffff0000, v219
	v_mul_f32_e32 v57, v57, v195
	v_cvt_pk_bf16_f32 v54, v54, v55
	v_cvt_pk_bf16_f32 v55, v56, v57
	global_store_dwordx2 v[176:177], v[54:55], off offset:1552
	v_mul_f32_e32 v194, v102, v186
	v_fmac_f32_e32 v194, v58, v98
	v_add_f32_e32 v58, v190, v194
	v_lshlrev_b32_e32 v195, 16, v220
	v_mul_f32_e32 v58, v58, v195
	v_mul_f32_e32 v194, v103, v186
	v_fmac_f32_e32 v194, v59, v99
	v_add_f32_e32 v59, v190, v194
	v_and_b32_e32 v195, 0xffff0000, v220
	v_mul_f32_e32 v59, v59, v195
	v_mul_f32_e32 v194, v104, v186
	v_fmac_f32_e32 v194, v60, v100
	v_add_f32_e32 v60, v190, v194
	v_lshlrev_b32_e32 v195, 16, v221
	v_mul_f32_e32 v60, v60, v195
	v_mul_f32_e32 v194, v105, v186
	v_fmac_f32_e32 v194, v61, v101
	v_add_f32_e32 v61, v190, v194
	v_and_b32_e32 v195, 0xffff0000, v221
	v_mul_f32_e32 v61, v61, v195
	v_cvt_pk_bf16_f32 v58, v58, v59
	v_cvt_pk_bf16_f32 v59, v60, v61
	global_store_dwordx2 v[176:177], v[58:59], off offset:1568
	v_mul_f32_e32 v194, v94, v186
	v_fmac_f32_e32 v194, v62, v90
	v_add_f32_e32 v62, v190, v194
	v_lshlrev_b32_e32 v195, 16, v222
	v_mul_f32_e32 v62, v62, v195
	v_mul_f32_e32 v194, v95, v186
	v_fmac_f32_e32 v194, v63, v91
	v_add_f32_e32 v63, v190, v194
	v_and_b32_e32 v195, 0xffff0000, v222
	v_mul_f32_e32 v63, v63, v195
	v_mul_f32_e32 v194, v96, v186
	v_fmac_f32_e32 v194, v64, v92
	v_add_f32_e32 v64, v190, v194
	v_lshlrev_b32_e32 v195, 16, v223
	v_mul_f32_e32 v64, v64, v195
	v_mul_f32_e32 v194, v97, v186
	v_fmac_f32_e32 v194, v65, v93
	v_add_f32_e32 v65, v190, v194
	v_and_b32_e32 v195, 0xffff0000, v223
	v_mul_f32_e32 v65, v65, v195
	v_cvt_pk_bf16_f32 v62, v62, v63
	v_cvt_pk_bf16_f32 v63, v64, v65
	global_store_dwordx2 v[176:177], v[62:63], off offset:1584
	v_mul_f32_e32 v194, v118, v187
	v_fmac_f32_e32 v194, v34, v114
	v_add_f32_e32 v34, v191, v194
	v_lshlrev_b32_e32 v195, 16, v224
	v_mul_f32_e32 v34, v34, v195
	v_mul_f32_e32 v194, v119, v187
	v_fmac_f32_e32 v194, v35, v115
	v_add_f32_e32 v35, v191, v194
	v_and_b32_e32 v195, 0xffff0000, v224
	v_mul_f32_e32 v35, v35, v195
	v_mul_f32_e32 v194, v120, v187
	v_fmac_f32_e32 v194, v36, v116
	v_add_f32_e32 v36, v191, v194
	v_lshlrev_b32_e32 v195, 16, v225
	v_mul_f32_e32 v36, v36, v195
	v_mul_f32_e32 v194, v121, v187
	v_fmac_f32_e32 v194, v37, v117
	v_add_f32_e32 v37, v191, v194
	v_and_b32_e32 v195, 0xffff0000, v225
	v_mul_f32_e32 v37, v37, v195
	v_cvt_pk_bf16_f32 v34, v34, v35
	v_cvt_pk_bf16_f32 v35, v36, v37
	global_store_dwordx2 v[178:179], v[34:35], off offset:1536
	v_mul_f32_e32 v194, v110, v187
	v_fmac_f32_e32 v194, v38, v106
	v_add_f32_e32 v38, v191, v194
	v_lshlrev_b32_e32 v195, 16, v226
	v_mul_f32_e32 v38, v38, v195
	v_mul_f32_e32 v194, v111, v187
	v_fmac_f32_e32 v194, v39, v107
	v_add_f32_e32 v39, v191, v194
	v_and_b32_e32 v195, 0xffff0000, v226
	v_mul_f32_e32 v39, v39, v195
	v_mul_f32_e32 v194, v112, v187
	v_fmac_f32_e32 v194, v40, v108
	v_add_f32_e32 v40, v191, v194
	v_lshlrev_b32_e32 v195, 16, v227
	v_mul_f32_e32 v40, v40, v195
	v_mul_f32_e32 v194, v113, v187
	v_fmac_f32_e32 v194, v41, v109
	v_add_f32_e32 v41, v191, v194
	v_and_b32_e32 v195, 0xffff0000, v227
	v_mul_f32_e32 v41, v41, v195
	v_cvt_pk_bf16_f32 v38, v38, v39
	v_cvt_pk_bf16_f32 v39, v40, v41
	global_store_dwordx2 v[178:179], v[38:39], off offset:1552
	v_mul_f32_e32 v194, v102, v187
	v_fmac_f32_e32 v194, v42, v98
	v_add_f32_e32 v42, v191, v194
	v_lshlrev_b32_e32 v195, 16, v228
	v_mul_f32_e32 v42, v42, v195
	v_mul_f32_e32 v194, v103, v187
	v_fmac_f32_e32 v194, v43, v99
	v_add_f32_e32 v43, v191, v194
	v_and_b32_e32 v195, 0xffff0000, v228
	v_mul_f32_e32 v43, v43, v195
	v_mul_f32_e32 v194, v104, v187
	v_fmac_f32_e32 v194, v44, v100
	v_add_f32_e32 v44, v191, v194
	v_lshlrev_b32_e32 v195, 16, v229
	v_mul_f32_e32 v44, v44, v195
	v_mul_f32_e32 v194, v105, v187
	v_fmac_f32_e32 v194, v45, v101
	v_add_f32_e32 v45, v191, v194
	v_and_b32_e32 v195, 0xffff0000, v229
	v_mul_f32_e32 v45, v45, v195
	v_cvt_pk_bf16_f32 v42, v42, v43
	v_cvt_pk_bf16_f32 v43, v44, v45
	global_store_dwordx2 v[178:179], v[42:43], off offset:1568
	v_mul_f32_e32 v194, v94, v187
	v_fmac_f32_e32 v194, v46, v90
	v_add_f32_e32 v46, v191, v194
	v_lshlrev_b32_e32 v195, 16, v230
	v_mul_f32_e32 v46, v46, v195
	v_mul_f32_e32 v194, v95, v187
	v_fmac_f32_e32 v194, v47, v91
	v_add_f32_e32 v47, v191, v194
	v_and_b32_e32 v195, 0xffff0000, v230
	v_mul_f32_e32 v47, v47, v195
	v_mul_f32_e32 v194, v96, v187
	v_fmac_f32_e32 v194, v48, v92
	v_add_f32_e32 v48, v191, v194
	v_lshlrev_b32_e32 v195, 16, v231
	v_mul_f32_e32 v48, v48, v195
	v_mul_f32_e32 v194, v97, v187
	v_fmac_f32_e32 v194, v49, v93
	v_add_f32_e32 v49, v191, v194
	v_and_b32_e32 v195, 0xffff0000, v231
	v_mul_f32_e32 v49, v49, v195
	v_cvt_pk_bf16_f32 v46, v46, v47
	v_cvt_pk_bf16_f32 v47, v48, v49
	global_store_dwordx2 v[178:179], v[46:47], off offset:1584
	v_mul_f32_e32 v194, v118, v188
	v_fmac_f32_e32 v194, v18, v114
	v_add_f32_e32 v18, v192, v194
	v_lshlrev_b32_e32 v195, 16, v232
	v_mul_f32_e32 v18, v18, v195
	v_mul_f32_e32 v194, v119, v188
	v_fmac_f32_e32 v194, v19, v115
	v_add_f32_e32 v19, v192, v194
	v_and_b32_e32 v195, 0xffff0000, v232
	v_mul_f32_e32 v19, v19, v195
	v_mul_f32_e32 v194, v120, v188
	v_fmac_f32_e32 v194, v20, v116
	v_add_f32_e32 v20, v192, v194
	v_lshlrev_b32_e32 v195, 16, v233
	v_mul_f32_e32 v20, v20, v195
	v_mul_f32_e32 v194, v121, v188
	v_fmac_f32_e32 v194, v21, v117
	v_add_f32_e32 v21, v192, v194
	v_and_b32_e32 v195, 0xffff0000, v233
	v_mul_f32_e32 v21, v21, v195
	v_cvt_pk_bf16_f32 v18, v18, v19
	v_cvt_pk_bf16_f32 v19, v20, v21
	global_store_dwordx2 v[182:183], v[18:19], off offset:1536
	v_mul_f32_e32 v194, v110, v188
	v_fmac_f32_e32 v194, v22, v106
	v_add_f32_e32 v22, v192, v194
	v_lshlrev_b32_e32 v195, 16, v234
	v_mul_f32_e32 v22, v22, v195
	v_mul_f32_e32 v194, v111, v188
	v_fmac_f32_e32 v194, v23, v107
	v_add_f32_e32 v23, v192, v194
	v_and_b32_e32 v195, 0xffff0000, v234
	v_mul_f32_e32 v23, v23, v195
	v_mul_f32_e32 v194, v112, v188
	v_fmac_f32_e32 v194, v24, v108
	v_add_f32_e32 v24, v192, v194
	v_lshlrev_b32_e32 v195, 16, v235
	v_mul_f32_e32 v24, v24, v195
	v_mul_f32_e32 v194, v113, v188
	v_fmac_f32_e32 v194, v25, v109
	v_add_f32_e32 v25, v192, v194
	v_and_b32_e32 v195, 0xffff0000, v235
	v_mul_f32_e32 v25, v25, v195
	v_cvt_pk_bf16_f32 v22, v22, v23
	v_cvt_pk_bf16_f32 v23, v24, v25
	global_store_dwordx2 v[182:183], v[22:23], off offset:1552
	v_mul_f32_e32 v194, v102, v188
	v_fmac_f32_e32 v194, v26, v98
	v_add_f32_e32 v26, v192, v194
	v_lshlrev_b32_e32 v195, 16, v236
	v_mul_f32_e32 v26, v26, v195
	v_mul_f32_e32 v194, v103, v188
	v_fmac_f32_e32 v194, v27, v99
	v_add_f32_e32 v27, v192, v194
	v_and_b32_e32 v195, 0xffff0000, v236
	v_mul_f32_e32 v27, v27, v195
	v_mul_f32_e32 v194, v104, v188
	v_fmac_f32_e32 v194, v28, v100
	v_add_f32_e32 v28, v192, v194
	v_lshlrev_b32_e32 v195, 16, v237
	v_mul_f32_e32 v28, v28, v195
	v_mul_f32_e32 v194, v105, v188
	v_fmac_f32_e32 v194, v29, v101
	v_add_f32_e32 v29, v192, v194
	v_and_b32_e32 v195, 0xffff0000, v237
	v_mul_f32_e32 v29, v29, v195
	v_cvt_pk_bf16_f32 v26, v26, v27
	v_cvt_pk_bf16_f32 v27, v28, v29
	global_store_dwordx2 v[182:183], v[26:27], off offset:1568
	v_mul_f32_e32 v194, v94, v188
	v_fmac_f32_e32 v194, v30, v90
	v_add_f32_e32 v30, v192, v194
	v_lshlrev_b32_e32 v195, 16, v238
	v_mul_f32_e32 v30, v30, v195
	v_mul_f32_e32 v194, v95, v188
	v_fmac_f32_e32 v194, v31, v91
	v_add_f32_e32 v31, v192, v194
	v_and_b32_e32 v195, 0xffff0000, v238
	v_mul_f32_e32 v31, v31, v195
	v_mul_f32_e32 v194, v96, v188
	v_fmac_f32_e32 v194, v32, v92
	v_add_f32_e32 v32, v192, v194
	v_lshlrev_b32_e32 v195, 16, v239
	v_mul_f32_e32 v32, v32, v195
	v_mul_f32_e32 v194, v97, v188
	v_fmac_f32_e32 v194, v33, v93
	v_add_f32_e32 v33, v192, v194
	v_and_b32_e32 v195, 0xffff0000, v239
	v_mul_f32_e32 v33, v33, v195
	v_cvt_pk_bf16_f32 v30, v30, v31
	v_cvt_pk_bf16_f32 v31, v32, v33
	global_store_dwordx2 v[182:183], v[30:31], off offset:1584
	v_mul_f32_e32 v194, v118, v189
	v_fmac_f32_e32 v194, v2, v114
	v_add_f32_e32 v2, v193, v194
	v_lshlrev_b32_e32 v195, 16, v240
	v_mul_f32_e32 v2, v2, v195
	v_mul_f32_e32 v194, v119, v189
	v_fmac_f32_e32 v194, v3, v115
	v_add_f32_e32 v3, v193, v194
	v_and_b32_e32 v195, 0xffff0000, v240
	v_mul_f32_e32 v3, v3, v195
	v_mul_f32_e32 v194, v120, v189
	v_fmac_f32_e32 v194, v4, v116
	v_add_f32_e32 v4, v193, v194
	v_lshlrev_b32_e32 v195, 16, v241
	v_mul_f32_e32 v4, v4, v195
	v_mul_f32_e32 v194, v121, v189
	v_fmac_f32_e32 v194, v5, v117
	v_add_f32_e32 v5, v193, v194
	v_and_b32_e32 v195, 0xffff0000, v241
	v_mul_f32_e32 v5, v5, v195
	v_cvt_pk_bf16_f32 v2, v2, v3
	v_cvt_pk_bf16_f32 v3, v4, v5
	global_store_dwordx2 v[184:185], v[2:3], off offset:1536
	v_mul_f32_e32 v194, v110, v189
	v_fmac_f32_e32 v194, v6, v106
	v_add_f32_e32 v6, v193, v194
	v_lshlrev_b32_e32 v195, 16, v246
	v_mul_f32_e32 v6, v6, v195
	v_mul_f32_e32 v194, v111, v189
	v_fmac_f32_e32 v194, v7, v107
	v_add_f32_e32 v7, v193, v194
	v_and_b32_e32 v195, 0xffff0000, v246
	v_mul_f32_e32 v7, v7, v195
	v_mul_f32_e32 v194, v112, v189
	v_fmac_f32_e32 v194, v8, v108
	v_add_f32_e32 v8, v193, v194
	v_lshlrev_b32_e32 v195, 16, v247
	v_mul_f32_e32 v8, v8, v195
	v_mul_f32_e32 v194, v113, v189
	v_fmac_f32_e32 v194, v9, v109
	v_add_f32_e32 v9, v193, v194
	v_and_b32_e32 v195, 0xffff0000, v247
	v_mul_f32_e32 v9, v9, v195
	v_cvt_pk_bf16_f32 v6, v6, v7
	v_cvt_pk_bf16_f32 v7, v8, v9
	global_store_dwordx2 v[184:185], v[6:7], off offset:1552
	v_mul_f32_e32 v194, v102, v189
	v_fmac_f32_e32 v194, v10, v98
	v_add_f32_e32 v10, v193, v194
	v_lshlrev_b32_e32 v195, 16, v252
	v_mul_f32_e32 v10, v10, v195
	v_mul_f32_e32 v194, v103, v189
	v_fmac_f32_e32 v194, v11, v99
	v_add_f32_e32 v11, v193, v194
	v_and_b32_e32 v195, 0xffff0000, v252
	v_mul_f32_e32 v11, v11, v195
	v_mul_f32_e32 v194, v104, v189
	v_fmac_f32_e32 v194, v12, v100
	v_add_f32_e32 v12, v193, v194
	v_lshlrev_b32_e32 v195, 16, v253
	v_mul_f32_e32 v12, v12, v195
	v_mul_f32_e32 v194, v105, v189
	v_fmac_f32_e32 v194, v13, v101
	v_add_f32_e32 v13, v193, v194
	v_and_b32_e32 v195, 0xffff0000, v253
	v_mul_f32_e32 v13, v13, v195
	v_cvt_pk_bf16_f32 v10, v10, v11
	v_cvt_pk_bf16_f32 v11, v12, v13
	global_store_dwordx2 v[184:185], v[10:11], off offset:1568
	v_mul_f32_e32 v194, v94, v189
	v_fmac_f32_e32 v194, v14, v90
	v_add_f32_e32 v14, v193, v194
	v_lshlrev_b32_e32 v195, 16, v254
	v_mul_f32_e32 v14, v14, v195
	v_mul_f32_e32 v194, v95, v189
	v_fmac_f32_e32 v194, v15, v91
	v_add_f32_e32 v15, v193, v194
	v_and_b32_e32 v195, 0xffff0000, v254
	v_mul_f32_e32 v15, v15, v195
	v_mul_f32_e32 v194, v96, v189
	v_fmac_f32_e32 v194, v16, v92
	v_add_f32_e32 v16, v193, v194
	v_lshlrev_b32_e32 v195, 16, v255
	v_mul_f32_e32 v16, v16, v195
	v_mul_f32_e32 v194, v97, v189
	v_fmac_f32_e32 v194, v17, v93
	v_add_f32_e32 v17, v193, v194
	v_and_b32_e32 v195, 0xffff0000, v255
	v_mul_f32_e32 v17, v17, v195
	v_cvt_pk_bf16_f32 v14, v14, v15
	v_cvt_pk_bf16_f32 v15, v16, v17
	global_store_dwordx2 v[184:185], v[14:15], off offset:1584
	s_barrier
	s_cbranch_scc0 .LBB0_779

.LBB0_849:
	v_mov_b32_e32 v43, v0
	s_ashr_i32 s5, s3, 31
	v_ashrrev_i32_e32 v44, 7, v43
	s_waitcnt vmcnt(7)
	v_add_u32_e32 v130, s2, v44
	v_ashrrev_i32_e32 v131, 31, v130
	v_and_b32_e32 v134, 31, v43
	s_waitcnt vmcnt(0)
	v_lshlrev_b64 v[2:3], 15, v[130:131]
	v_bfe_u32 v135, v43, 5, 1
	v_lshl_add_u64 v[2:3], s[56:57], 0, v[2:3]
	v_lshlrev_b32_e32 v154, 8, v134
	v_lshl_add_u64 v[2:3], v[2:3], 0, v[154:155]
	v_lshlrev_b32_e32 v154, 4, v135
	v_lshl_add_u64 v[18:19], v[2:3], 0, v[154:155]
	v_add_co_u32_e32 v20, vcc, s14, v18
	v_ashrrev_i32_e32 v45, 2, v43
	s_nop 0
	v_addc_co_u32_e32 v21, vcc, 0, v19, vcc
	v_add_co_u32_e32 v22, vcc, s17, v18
	global_load_dwordx4 v[2:5], v[18:19], off
	global_load_dwordx4 v[6:9], v[20:21], off
	v_addc_co_u32_e32 v23, vcc, 0, v19, vcc
	v_add_co_u32_e32 v24, vcc, s30, v18
	global_load_dwordx4 v[10:13], v[22:23], off
	s_nop 0
	v_addc_co_u32_e32 v25, vcc, 0, v19, vcc
	global_load_dwordx4 v[14:17], v[24:25], off
	global_load_dwordx4 v[114:117], v[18:19], off offset:32
	global_load_dwordx4 v[118:121], v[20:21], off offset:32
	global_load_dwordx4 v[122:125], v[22:23], off offset:32
	global_load_dwordx4 v[126:129], v[24:25], off offset:32
	global_load_dwordx4 v[102:105], v[20:21], off offset:64
	global_load_dwordx4 v[106:109], v[22:23], off offset:64
	global_load_dwordx4 v[110:113], v[24:25], off offset:64
	global_load_dwordx4 v[90:93], v[20:21], off offset:96
	global_load_dwordx4 v[94:97], v[22:23], off offset:96
	global_load_dwordx4 v[98:101], v[24:25], off offset:96
	global_load_dwordx4 v[82:85], v[22:23], off offset:128
	global_load_dwordx4 v[86:89], v[24:25], off offset:128
	global_load_dwordx4 v[74:77], v[22:23], off offset:160
	global_load_dwordx4 v[78:81], v[24:25], off offset:160
	global_load_dwordx4 v[70:73], v[24:25], off offset:192
	global_load_dwordx4 v[66:69], v[24:25], off offset:224
	v_add_u32_e32 v18, s3, v45
	v_ashrrev_i32_e32 v19, 31, v18
	v_lshlrev_b32_e32 v20, 6, v43
	v_lshlrev_b64 v[18:19], 12, v[18:19]
	v_and_b32_e32 v46, 0xc0, v20
	v_lshl_add_u64 v[18:19], s[60:61], 0, v[18:19]
	v_lshlrev_b32_e32 v20, 1, v46
	v_mov_b32_e32 v21, v155
	v_lshl_add_u64 v[34:35], v[18:19], 0, v[20:21]
	global_load_dwordx4 v[18:21], v[34:35], off offset:3632
	global_load_dwordx4 v[22:25], v[34:35], off offset:3616
	global_load_dwordx4 v[26:29], v[34:35], off offset:3600
	global_load_dwordx4 v[30:33], v[34:35], off offset:3584
	global_load_dwordx4 v[36:39], v[34:35], off offset:3680
	global_load_dwordx4 v[176:179], v[34:35], off offset:3664
	global_load_dwordx4 v[48:51], v[34:35], off offset:3648
	global_load_dwordx4 v[182:185], v[34:35], off offset:3696
	v_and_b32_e32 v215, 31, v0
	v_add_u32_e32 v215, s3, v215
	v_lshlrev_b32_e32 v215, 12, v215
	v_and_b32_e32 v245, 0x1c0, v0
	v_add_u32_e32 v215, v215, v245
	v_bfe_u32 v245, v0, 5, 1
	v_lshl_add_u32 v215, v245, 3, v215
	global_load_dwordx2 v[216:217], v215, s[60:61] offset:3072
	global_load_dwordx2 v[218:219], v215, s[60:61] offset:3088
	global_load_dwordx2 v[220:221], v215, s[60:61] offset:3104
	global_load_dwordx2 v[222:223], v215, s[60:61] offset:3120
	s_add_u32 s98, s60, 0x20000
	s_addc_u32 s99, s61, 0
	global_load_dwordx2 v[224:225], v215, s[98:99] offset:3072
	global_load_dwordx2 v[226:227], v215, s[98:99] offset:3088
	global_load_dwordx2 v[228:229], v215, s[98:99] offset:3104
	global_load_dwordx2 v[230:231], v215, s[98:99] offset:3120
	s_add_u32 s100, s60, 0x40000
	s_addc_u32 s101, s61, 0
	global_load_dwordx2 v[232:233], v215, s[100:101] offset:3072
	global_load_dwordx2 v[234:235], v215, s[100:101] offset:3088
	global_load_dwordx2 v[236:237], v215, s[100:101] offset:3104
	global_load_dwordx2 v[238:239], v215, s[100:101] offset:3120
	s_add_u32 s98, s60, 0x60000
	s_addc_u32 s99, s61, 0
	global_load_dwordx2 v[240:241], v215, s[98:99] offset:3072
	global_load_dwordx2 v[246:247], v215, s[98:99] offset:3088
	global_load_dwordx2 v[252:253], v215, s[98:99] offset:3104
	global_load_dwordx2 v[254:255], v215, s[98:99] offset:3120
	v_lshrrev_b32_e32 v42, 5, v43
	s_add_i32 s4, s4, s46
	s_waitcnt vmcnt(23)
	v_lshlrev_b32_e32 v144, 16, v18
	s_waitcnt vmcnt(22)
	v_lshlrev_b32_e32 v150, 16, v22
	s_waitcnt vmcnt(21)
	v_lshlrev_b32_e32 v168, 16, v26
	s_waitcnt vmcnt(20)
	v_lshlrev_b32_e32 v174, 16, v30
	v_and_b32_e32 v173, 0xffff0000, v30
	v_add_f32_e32 v30, 0, v174
	v_lshlrev_b32_e32 v172, 16, v31
	v_add_f32_e32 v30, v30, v173
	v_and_b32_e32 v171, 0xffff0000, v31
	v_mul_f32_e32 v31, v173, v173
	v_add_f32_e32 v30, v30, v172
	v_lshlrev_b32_e32 v170, 16, v32
	v_fmac_f32_e32 v31, v174, v174
	v_add_f32_e32 v30, v30, v171
	v_and_b32_e32 v169, 0xffff0000, v32
	v_fmac_f32_e32 v31, v172, v172
	v_add_f32_e32 v30, v30, v170
	v_lshlrev_b32_e32 v167, 16, v33
	v_fmac_f32_e32 v31, v171, v171
	v_add_f32_e32 v30, v30, v169
	v_and_b32_e32 v165, 0xffff0000, v33
	v_fmac_f32_e32 v31, v170, v170
	v_add_f32_e32 v30, v30, v167
	v_fmac_f32_e32 v31, v169, v169
	v_add_f32_e32 v30, v30, v165
	v_fmac_f32_e32 v31, v167, v167
	v_and_b32_e32 v166, 0xffff0000, v26
	v_add_f32_e32 v26, v30, v168
	v_fmac_f32_e32 v31, v165, v165
	v_lshlrev_b32_e32 v164, 16, v27
	v_add_f32_e32 v26, v26, v166
	v_and_b32_e32 v153, 0xffff0000, v27
	v_fmac_f32_e32 v31, v168, v168
	v_add_f32_e32 v26, v26, v164
	v_lshlrev_b32_e32 v152, 16, v28
	v_fmac_f32_e32 v31, v166, v166
	v_add_f32_e32 v26, v26, v153
	v_and_b32_e32 v151, 0xffff0000, v28
	v_fmac_f32_e32 v31, v164, v164
	v_add_f32_e32 v26, v26, v152
	v_lshlrev_b32_e32 v148, 16, v29
	v_fmac_f32_e32 v31, v153, v153
	v_add_f32_e32 v26, v26, v151
	v_and_b32_e32 v146, 0xffff0000, v29
	v_fmac_f32_e32 v31, v152, v152
	v_add_f32_e32 v26, v26, v148
	v_fmac_f32_e32 v31, v151, v151
	v_add_f32_e32 v26, v26, v146
	v_fmac_f32_e32 v31, v148, v148
	v_and_b32_e32 v149, 0xffff0000, v22
	v_add_f32_e32 v22, v26, v150
	v_fmac_f32_e32 v31, v146, v146
	v_lshlrev_b32_e32 v147, 16, v23
	v_add_f32_e32 v22, v22, v149
	v_and_b32_e32 v145, 0xffff0000, v23
	v_fmac_f32_e32 v31, v150, v150
	v_add_f32_e32 v22, v22, v147
	v_lshlrev_b32_e32 v143, 16, v24
	v_fmac_f32_e32 v31, v149, v149
	v_add_f32_e32 v22, v22, v145
	v_and_b32_e32 v141, 0xffff0000, v24
	v_fmac_f32_e32 v31, v147, v147
	v_add_f32_e32 v22, v22, v143
	v_lshlrev_b32_e32 v139, 16, v25
	v_fmac_f32_e32 v31, v145, v145
	v_add_f32_e32 v22, v22, v141
	v_and_b32_e32 v137, 0xffff0000, v25
	v_fmac_f32_e32 v31, v143, v143
	v_add_f32_e32 v22, v22, v139
	v_fmac_f32_e32 v31, v141, v141
	v_add_f32_e32 v22, v22, v137
	v_fmac_f32_e32 v31, v139, v139
	v_and_b32_e32 v142, 0xffff0000, v18
	v_add_f32_e32 v18, v22, v144
	v_fmac_f32_e32 v31, v137, v137
	v_lshlrev_b32_e32 v140, 16, v19
	v_add_f32_e32 v18, v18, v142
	v_and_b32_e32 v138, 0xffff0000, v19
	v_fmac_f32_e32 v31, v144, v144
	v_add_f32_e32 v18, v18, v140
	v_lshlrev_b32_e32 v133, 16, v20
	v_fmac_f32_e32 v31, v142, v142
	v_add_f32_e32 v18, v18, v138
	v_and_b32_e32 v131, 0xffff0000, v20
	v_fmac_f32_e32 v31, v140, v140
	v_add_f32_e32 v18, v18, v133
	v_lshlrev_b32_e32 v64, 16, v21
	v_fmac_f32_e32 v31, v138, v138
	v_add_f32_e32 v18, v18, v131
	v_and_b32_e32 v62, 0xffff0000, v21
	v_fmac_f32_e32 v31, v133, v133
	v_add_f32_e32 v18, v18, v64
	v_fmac_f32_e32 v31, v131, v131
	v_add_f32_e32 v18, v18, v62
	s_waitcnt vmcnt(17)
	v_lshlrev_b32_e32 v136, 16, v48
	v_fmac_f32_e32 v31, v64, v64
	v_and_b32_e32 v132, 0xffff0000, v48
	v_add_f32_e32 v18, v18, v136
	v_fmac_f32_e32 v31, v62, v62
	v_lshlrev_b32_e32 v65, 16, v49
	v_add_f32_e32 v18, v18, v132
	v_and_b32_e32 v63, 0xffff0000, v49
	v_fmac_f32_e32 v31, v136, v136
	v_add_f32_e32 v18, v18, v65
	v_lshlrev_b32_e32 v60, 16, v50
	v_fmac_f32_e32 v31, v132, v132
	v_add_f32_e32 v18, v18, v63
	v_and_b32_e32 v59, 0xffff0000, v50
	v_fmac_f32_e32 v31, v65, v65
	v_add_f32_e32 v18, v18, v60
	v_lshlrev_b32_e32 v57, 16, v51
	v_fmac_f32_e32 v31, v63, v63
	v_add_f32_e32 v18, v18, v59
	v_and_b32_e32 v55, 0xffff0000, v51
	v_fmac_f32_e32 v31, v60, v60
	v_add_f32_e32 v18, v18, v57
	v_fmac_f32_e32 v31, v59, v59
	v_add_f32_e32 v18, v18, v55
	v_lshlrev_b32_e32 v61, 16, v176
	v_fmac_f32_e32 v31, v57, v57
	v_and_b32_e32 v58, 0xffff0000, v176
	v_add_f32_e32 v18, v18, v61
	v_fmac_f32_e32 v31, v55, v55
	v_lshlrev_b32_e32 v56, 16, v177
	v_add_f32_e32 v18, v18, v58
	v_and_b32_e32 v54, 0xffff0000, v177
	v_fmac_f32_e32 v31, v61, v61
	v_add_f32_e32 v18, v18, v56
	v_lshlrev_b32_e32 v53, 16, v178
	v_fmac_f32_e32 v31, v58, v58
	v_add_f32_e32 v18, v18, v54
	v_and_b32_e32 v51, 0xffff0000, v178
	v_fmac_f32_e32 v31, v56, v56
	v_add_f32_e32 v18, v18, v53
	v_lshlrev_b32_e32 v49, 16, v179
	v_fmac_f32_e32 v31, v54, v54
	v_add_f32_e32 v18, v18, v51
	v_and_b32_e32 v47, 0xffff0000, v179
	v_fmac_f32_e32 v31, v53, v53
	v_add_f32_e32 v18, v18, v49
	v_fmac_f32_e32 v31, v51, v51
	v_add_f32_e32 v18, v18, v47
	v_lshlrev_b32_e32 v52, 16, v36
	v_fmac_f32_e32 v31, v49, v49
	v_and_b32_e32 v50, 0xffff0000, v36
	v_add_f32_e32 v18, v18, v52
	v_fmac_f32_e32 v31, v47, v47
	v_lshlrev_b32_e32 v48, 16, v37
	v_add_f32_e32 v18, v18, v50
	v_fmac_f32_e32 v31, v52, v52
	v_add_f32_e32 v18, v18, v48
	v_and_b32_e32 v37, 0xffff0000, v37
	v_fmac_f32_e32 v31, v50, v50
	v_lshlrev_b32_e32 v34, 16, v38
	v_mov_b32_e32 v35, v37
	v_add_f32_e32 v20, v18, v37
	v_fmac_f32_e32 v31, v48, v48
	v_and_b32_e32 v24, 0xffff0000, v38
	v_pk_mul_f32 v[18:19], v[34:35], v[34:35]
	v_add_f32_e32 v20, v20, v34
	v_lshlrev_b32_e32 v25, 16, v39
	v_add_f32_e32 v19, v19, v31
	v_add_f32_e32 v20, v20, v24
	v_add_f32_e32 v21, v18, v19
	v_pk_mul_f32 v[18:19], v[24:25], v[24:25]
	v_add_f32_e32 v20, v20, v25
	v_and_b32_e32 v33, 0xffff0000, v39
	v_add_f32_e32 v18, v18, v21
	s_waitcnt vmcnt(16)
	v_lshlrev_b32_e32 v28, 16, v182
	v_mov_b32_e32 v29, v33
	v_add_f32_e32 v20, v20, v33
	v_add_f32_e32 v21, v19, v18
	v_and_b32_e32 v22, 0xffff0000, v182
	v_pk_mul_f32 v[18:19], v[28:29], v[28:29]
	v_add_f32_e32 v20, v20, v28
	v_lshlrev_b32_e32 v23, 16, v183
	v_add_f32_e32 v19, v19, v21
	v_add_f32_e32 v20, v20, v22
	v_add_f32_e32 v21, v18, v19
	v_pk_mul_f32 v[18:19], v[22:23], v[22:23]
	v_add_f32_e32 v29, v20, v23
	v_and_b32_e32 v31, 0xffff0000, v183
	v_add_f32_e32 v18, v18, v21
	v_lshlrev_b32_e32 v26, 16, v184
	v_mov_b32_e32 v27, v31
	v_add_f32_e32 v29, v29, v31
	v_and_b32_e32 v36, s0, v38
	v_add_f32_e32 v18, v19, v18
	v_and_b32_e32 v20, 0xffff0000, v184
	v_pk_mul_f32 v[38:39], v[26:27], v[26:27]
	v_add_f32_e32 v27, v29, v26
	v_lshlrev_b32_e32 v21, 16, v185
	v_add_f32_e32 v18, v39, v18
	v_add_f32_e32 v27, v27, v20
	v_and_b32_e32 v29, 64, v181
	v_add_f32_e32 v18, v38, v18
	v_pk_mul_f32 v[40:41], v[20:21], v[20:21]
	v_add_f32_e32 v39, v27, v21
	v_xor_b32_e32 v27, 1, v181
	v_add_u32_e32 v29, 64, v29
	v_and_b32_e32 v19, 0xffff0000, v185
	v_add_f32_e32 v18, v40, v18
	v_cmp_lt_i32_e32 vcc, v27, v29
	v_add_f32_e32 v18, v41, v18
	v_mul_f32_e32 v38, v19, v19
	v_cndmask_b32_e32 v27, v181, v27, vcc
	v_lshlrev_b32_e32 v27, 2, v27
	v_pk_add_f32 v[38:39], v[38:39], v[18:19]
	ds_bpermute_b32 v41, v27, v39
	ds_bpermute_b32 v40, v27, v38
	v_xor_b32_e32 v35, 2, v181
	v_cmp_lt_i32_e32 vcc, v35, v29
	v_and_b32_e32 v30, s0, v182
	v_mov_b32_e32 v32, v36
	v_cndmask_b32_e32 v29, v181, v35, vcc
	v_lshlrev_b32_e32 v29, 2, v29
	s_waitcnt lgkmcnt(0)
	v_pk_add_f32 v[38:39], v[38:39], v[40:41]
	ds_bpermute_b32 v41, v29, v39
	ds_bpermute_b32 v40, v29, v38
	s_waitcnt lgkmcnt(0)
	v_pk_add_f32 v[40:41], v[38:39], v[40:41]
	s_nop 0
	v_pk_mul_f32 v[38:39], v[40:41], s[22:23] op_sel_hi:[1,0]
	v_pk_fma_f32 v[36:37], v[40:41], s[22:23], v[36:37] op_sel_hi:[1,0,1] neg_lo:[1,0,0] neg_hi:[1,0,0]
	v_fma_f32 v18, -v39, v39, v38
	v_max_f32_e32 v18, 0, v18
	v_add_f32_e32 v18, 0x358637bd, v18
	v_cmp_gt_f32_e32 vcc, s33, v18
	v_mul_f32_e32 v27, 0x4b800000, v18
	v_sub_f32_e32 v29, v174, v39
	v_cndmask_b32_e32 v18, v18, v27, vcc
	v_rsq_f32_e32 v18, v18
	v_sub_f32_e32 v19, v19, v39
	v_mul_f32_e32 v27, 0x45800000, v18
	v_cndmask_b32_e32 v18, v18, v27, vcc
	v_mul_f32_e32 v29, v29, v18
	v_lshlrev_b32_e32 v27, 1, v45
	v_bfe_u32 v35, v29, 16, 1
	v_ashrrev_i32_e32 v45, 1, v43
	v_and_b32_e32 v27, 14, v27
	v_add3_u32 v29, v29, v35, s15
	v_lshl_add_u32 v35, v46, 8, 32
	v_and_b32_e32 v46, -16, v45
	v_add3_u32 v174, v35, v46, v27
	ds_write_b16_d16_hi v174, v29 offset:55296
	v_sub_f32_e32 v29, v173, v39
	v_mul_f32_e32 v29, v29, v18
	v_bfe_u32 v173, v29, 16, 1
	v_add3_u32 v29, v29, v173, s15
	v_bitop3_b32 v173, v45, 16, -16 bitop3:0x6c
	v_add3_u32 v175, v35, v173, v27
	ds_write_b16_d16_hi v175, v29 offset:55552
	v_sub_f32_e32 v29, v172, v39
	v_mul_f32_e32 v29, v29, v18
	v_bfe_u32 v172, v29, 16, 1
	v_add3_u32 v29, v29, v172, s15
	v_bitop3_b32 v172, v45, 32, -16 bitop3:0x6c
	v_add3_u32 v176, v35, v172, v27
	ds_write_b16_d16_hi v176, v29 offset:55808
	v_sub_f32_e32 v29, v171, v39
	v_mul_f32_e32 v29, v29, v18
	v_bfe_u32 v171, v29, 16, 1
	v_add3_u32 v29, v29, v171, s15
	v_bitop3_b32 v171, v45, 48, -16 bitop3:0x6c
	v_add3_u32 v177, v35, v171, v27
	ds_write_b16_d16_hi v177, v29 offset:56064
	v_sub_f32_e32 v29, v170, v39
	v_mul_f32_e32 v29, v29, v18
	v_bfe_u32 v170, v29, 16, 1
	v_add3_u32 v29, v29, v170, s15
	v_bitop3_b32 v170, v45, 64, -16 bitop3:0x6c
	v_add3_u32 v178, v35, v170, v27
	ds_write_b16_d16_hi v178, v29 offset:56320
	v_sub_f32_e32 v29, v169, v39
	v_mul_f32_e32 v29, v29, v18
	v_bfe_u32 v169, v29, 16, 1
	v_add3_u32 v29, v29, v169, s15
	v_bitop3_b32 v169, v45, s34, -16 bitop3:0x6c
	v_add3_u32 v179, v35, v169, v27
	ds_write_b16_d16_hi v179, v29 offset:56576
	v_sub_f32_e32 v29, v167, v39
	v_mul_f32_e32 v29, v29, v18
	v_bfe_u32 v167, v29, 16, 1
	v_add3_u32 v29, v29, v167, s15
	v_bitop3_b32 v167, v45, s31, -16 bitop3:0x6c
	v_add3_u32 v182, v35, v167, v27
	ds_write_b16_d16_hi v182, v29 offset:56832
	v_sub_f32_e32 v29, v165, v39
	v_mul_f32_e32 v29, v29, v18
	v_bfe_u32 v165, v29, 16, 1
	v_add3_u32 v29, v29, v165, s15
	v_bitop3_b32 v165, v45, s13, -16 bitop3:0x6c
	v_add3_u32 v183, v35, v165, v27
	ds_write_b16_d16_hi v183, v29 offset:57088
	v_sub_f32_e32 v29, v168, v39
	v_mul_f32_e32 v29, v29, v18
	v_bfe_u32 v168, v29, 16, 1
	v_add3_u32 v29, v29, v168, s15
	v_bitop3_b32 v168, v45, s12, -16 bitop3:0x6c
	v_add3_u32 v184, v35, v168, v27
	ds_write_b16_d16_hi v184, v29 offset:57344
	v_sub_f32_e32 v29, v166, v39
	v_mul_f32_e32 v29, v29, v18
	v_bfe_u32 v166, v29, 16, 1
	v_add3_u32 v29, v29, v166, s15
	v_bitop3_b32 v166, v45, s35, -16 bitop3:0x6c
	v_add3_u32 v185, v35, v166, v27
	ds_write_b16_d16_hi v185, v29 offset:57600
	v_sub_f32_e32 v29, v164, v39
	v_mul_f32_e32 v29, v29, v18
	v_bfe_u32 v164, v29, 16, 1
	v_add3_u32 v29, v29, v164, s15
	v_bitop3_b32 v164, v45, s38, -16 bitop3:0x6c
	v_add3_u32 v186, v35, v164, v27
	ds_write_b16_d16_hi v186, v29 offset:57856
	v_sub_f32_e32 v29, v153, v39
	v_mul_f32_e32 v29, v29, v18
	v_bfe_u32 v153, v29, 16, 1
	v_add3_u32 v29, v29, v153, s15
	v_bitop3_b32 v153, v45, s39, -16 bitop3:0x6c
	v_add3_u32 v187, v35, v153, v27
	ds_write_b16_d16_hi v187, v29 offset:58112
	v_sub_f32_e32 v29, v152, v39
	v_mul_f32_e32 v29, v29, v18
	v_bfe_u32 v152, v29, 16, 1
	v_add3_u32 v29, v29, v152, s15
	v_bitop3_b32 v152, v45, s16, -16 bitop3:0x6c
	v_add3_u32 v188, v35, v152, v27
	ds_write_b16_d16_hi v188, v29 offset:58368
	v_sub_f32_e32 v29, v151, v39
	v_mul_f32_e32 v29, v29, v18
	v_bfe_u32 v151, v29, 16, 1
	v_add3_u32 v29, v29, v151, s15
	v_bitop3_b32 v151, v45, s40, -16 bitop3:0x6c
	v_add3_u32 v189, v35, v151, v27
	ds_write_b16_d16_hi v189, v29 offset:58624
	v_sub_f32_e32 v29, v148, v39
	v_mul_f32_e32 v29, v29, v18
	v_bfe_u32 v148, v29, 16, 1
	v_add3_u32 v29, v29, v148, s15
	v_bitop3_b32 v148, v45, s41, -16 bitop3:0x6c
	v_add3_u32 v190, v35, v148, v27
	ds_write_b16_d16_hi v190, v29 offset:58880
	v_sub_f32_e32 v29, v146, v39
	v_mul_f32_e32 v29, v29, v18
	v_bfe_u32 v146, v29, 16, 1
	v_bitop3_b32 v45, v45, s42, -16 bitop3:0x6c
	v_add_u32_e32 v38, 0xd800, v35
	v_add3_u32 v29, v29, v146, s15
	v_add3_u32 v35, v35, v45, v27
	ds_write_b16_d16_hi v35, v29 offset:59136
	v_sub_f32_e32 v29, v150, v39
	v_mul_f32_e32 v29, v29, v18
	v_bfe_u32 v146, v29, 16, 1
	v_add3_u32 v29, v29, v146, s15
	ds_write_b16_d16_hi v174, v29 offset:59392
	v_sub_f32_e32 v29, v149, v39
	v_mul_f32_e32 v29, v29, v18
	v_bfe_u32 v146, v29, 16, 1
	v_add3_u32 v29, v29, v146, s15
	ds_write_b16_d16_hi v175, v29 offset:59648
	v_sub_f32_e32 v29, v147, v39
	v_mul_f32_e32 v29, v29, v18
	v_bfe_u32 v146, v29, 16, 1
	v_add3_u32 v29, v29, v146, s15
	ds_write_b16_d16_hi v176, v29 offset:59904
	v_sub_f32_e32 v29, v145, v39
	v_mul_f32_e32 v29, v29, v18
	v_bfe_u32 v145, v29, 16, 1
	v_add3_u32 v29, v29, v145, s15
	ds_write_b16_d16_hi v177, v29 offset:60160
	v_sub_f32_e32 v29, v143, v39
	v_mul_f32_e32 v29, v29, v18
	v_bfe_u32 v143, v29, 16, 1
	v_add3_u32 v29, v29, v143, s15
	ds_write_b16_d16_hi v178, v29 offset:60416
	v_sub_f32_e32 v29, v141, v39
	v_mul_f32_e32 v29, v29, v18
	v_bfe_u32 v141, v29, 16, 1
	v_add3_u32 v29, v29, v141, s15
	ds_write_b16_d16_hi v179, v29 offset:60672
	v_sub_f32_e32 v29, v139, v39
	v_mul_f32_e32 v29, v29, v18
	v_bfe_u32 v139, v29, 16, 1
	v_add3_u32 v29, v29, v139, s15
	ds_write_b16_d16_hi v182, v29 offset:60928
	v_sub_f32_e32 v29, v137, v39
	v_mul_f32_e32 v29, v29, v18
	v_bfe_u32 v137, v29, 16, 1
	v_add3_u32 v29, v29, v137, s15
	ds_write_b16_d16_hi v183, v29 offset:61184
	v_sub_f32_e32 v29, v144, v39
	v_mul_f32_e32 v29, v29, v18
	v_bfe_u32 v137, v29, 16, 1
	v_add3_u32 v29, v29, v137, s15
	ds_write_b16_d16_hi v184, v29 offset:61440
	v_sub_f32_e32 v29, v142, v39
	v_mul_f32_e32 v29, v29, v18
	v_bfe_u32 v137, v29, 16, 1
	v_add3_u32 v29, v29, v137, s15
	ds_write_b16_d16_hi v185, v29 offset:61696
	v_sub_f32_e32 v29, v140, v39
	v_mul_f32_e32 v29, v29, v18
	v_bfe_u32 v137, v29, 16, 1
	v_add3_u32 v29, v29, v137, s15
	ds_write_b16_d16_hi v186, v29 offset:61952
	v_sub_f32_e32 v29, v138, v39
	v_mul_f32_e32 v29, v29, v18
	v_bfe_u32 v137, v29, 16, 1
	v_add3_u32 v29, v29, v137, s15
	ds_write_b16_d16_hi v187, v29 offset:62208
	v_sub_f32_e32 v29, v133, v39
	v_mul_f32_e32 v29, v29, v18
	v_bfe_u32 v133, v29, 16, 1
	v_add3_u32 v29, v29, v133, s15
	ds_write_b16_d16_hi v188, v29 offset:62464
	v_sub_f32_e32 v29, v131, v39
	v_mul_f32_e32 v29, v29, v18
	v_bfe_u32 v131, v29, 16, 1
	v_add3_u32 v29, v29, v131, s15
	ds_write_b16_d16_hi v189, v29 offset:62720
	v_sub_f32_e32 v29, v64, v39
	v_mul_f32_e32 v29, v29, v18
	v_bfe_u32 v64, v29, 16, 1
	v_add3_u32 v29, v29, v64, s15
	ds_write_b16_d16_hi v190, v29 offset:62976
	v_sub_f32_e32 v29, v62, v39
	v_mul_f32_e32 v29, v29, v18
	v_bfe_u32 v62, v29, 16, 1
	v_add3_u32 v29, v29, v62, s15
	ds_write_b16_d16_hi v35, v29 offset:63232
	v_sub_f32_e32 v29, v136, v39
	v_mul_f32_e32 v29, v29, v18
	v_bfe_u32 v35, v29, 16, 1
	v_add3_u32 v29, v29, v35, s15
	ds_write_b16_d16_hi v174, v29 offset:63488
	v_sub_f32_e32 v29, v132, v39
	v_mul_f32_e32 v29, v29, v18
	v_bfe_u32 v35, v29, 16, 1
	v_add3_u32 v29, v29, v35, s15
	ds_write_b16_d16_hi v175, v29 offset:63744
	v_sub_f32_e32 v29, v65, v39
	v_mul_f32_e32 v29, v29, v18
	v_bfe_u32 v35, v29, 16, 1
	v_add3_u32 v29, v29, v35, s15
	ds_write_b16_d16_hi v176, v29 offset:64000
	v_sub_f32_e32 v29, v63, v39
	v_mul_f32_e32 v29, v29, v18
	v_bfe_u32 v35, v29, 16, 1
	v_add3_u32 v29, v29, v35, s15
	ds_write_b16_d16_hi v177, v29 offset:64256
	v_sub_f32_e32 v29, v60, v39
	v_mul_f32_e32 v29, v29, v18
	v_bfe_u32 v35, v29, 16, 1
	v_add3_u32 v29, v29, v35, s15
	ds_write_b16_d16_hi v178, v29 offset:64512
	v_sub_f32_e32 v29, v59, v39
	v_mul_f32_e32 v29, v29, v18
	v_bfe_u32 v35, v29, 16, 1
	v_add3_u32 v29, v29, v35, s15
	ds_write_b16_d16_hi v179, v29 offset:64768
	v_sub_f32_e32 v29, v57, v39
	v_mul_f32_e32 v29, v29, v18
	v_bfe_u32 v35, v29, 16, 1
	v_add3_u32 v29, v29, v35, s15
	ds_write_b16_d16_hi v182, v29 offset:65024
	v_sub_f32_e32 v29, v55, v39
	v_mul_f32_e32 v29, v29, v18
	v_bfe_u32 v35, v29, 16, 1
	v_add3_u32 v29, v29, v35, s15
	ds_write_b16_d16_hi v183, v29 offset:65280
	v_sub_f32_e32 v29, v61, v39
	v_mul_f32_e32 v29, v29, v18
	v_bfe_u32 v35, v29, 16, 1
	v_add3_u32 v29, v29, v35, s15
	v_add3_u32 v35, v38, v168, v27
	ds_write_b16_d16_hi v35, v29 offset:10240
	v_sub_f32_e32 v29, v58, v39
	v_mul_f32_e32 v29, v29, v18
	v_bfe_u32 v55, v29, 16, 1
	v_add3_u32 v29, v29, v55, s15
	v_add3_u32 v55, v38, v166, v27
	ds_write_b16_d16_hi v55, v29 offset:10496
	v_sub_f32_e32 v29, v56, v39
	v_mul_f32_e32 v29, v29, v18
	v_bfe_u32 v56, v29, 16, 1
	v_add3_u32 v29, v29, v56, s15
	v_add3_u32 v56, v38, v164, v27
	ds_write_b16_d16_hi v56, v29 offset:10752
	v_sub_f32_e32 v29, v54, v39
	v_mul_f32_e32 v29, v29, v18
	v_bfe_u32 v54, v29, 16, 1
	v_add3_u32 v29, v29, v54, s15
	v_add3_u32 v54, v38, v153, v27
	ds_write_b16_d16_hi v54, v29 offset:11008
	v_sub_f32_e32 v29, v53, v39
	v_mul_f32_e32 v29, v29, v18
	v_bfe_u32 v53, v29, 16, 1
	v_add3_u32 v29, v29, v53, s15
	v_add3_u32 v53, v38, v152, v27
	ds_write_b16_d16_hi v53, v29 offset:11264
	v_sub_f32_e32 v29, v51, v39
	v_mul_f32_e32 v29, v29, v18
	v_bfe_u32 v51, v29, 16, 1
	v_add3_u32 v29, v29, v51, s15
	v_add3_u32 v51, v38, v151, v27
	ds_write_b16_d16_hi v51, v29 offset:11520
	v_sub_f32_e32 v29, v49, v39
	v_mul_f32_e32 v29, v29, v18
	v_bfe_u32 v49, v29, 16, 1
	v_add3_u32 v29, v29, v49, s15
	v_add3_u32 v49, v38, v148, v27
	ds_write_b16_d16_hi v49, v29 offset:11776
	v_sub_f32_e32 v29, v47, v39
	v_mul_f32_e32 v29, v29, v18
	v_bfe_u32 v47, v29, 16, 1
	v_add3_u32 v29, v29, v47, s15
	v_add3_u32 v45, v38, v45, v27
	ds_write_b16_d16_hi v45, v29 offset:12032
	v_sub_f32_e32 v29, v52, v39
	v_mul_f32_e32 v29, v29, v18
	v_bfe_u32 v47, v29, 16, 1
	v_add3_u32 v29, v29, v47, s15
	v_add3_u32 v46, v38, v46, v27
	ds_write_b16_d16_hi v46, v29 offset:12288
	v_sub_f32_e32 v29, v50, v39
	v_mul_f32_e32 v29, v29, v18
	v_bfe_u32 v46, v29, 16, 1
	v_add3_u32 v29, v29, v46, s15
	v_add3_u32 v46, v38, v173, v27
	ds_write_b16_d16_hi v46, v29 offset:12544
	v_sub_f32_e32 v29, v48, v39
	v_mul_f32_e32 v29, v29, v18
	v_bfe_u32 v46, v29, 16, 1
	v_add3_u32 v29, v29, v46, s15
	v_add3_u32 v46, v38, v172, v27
	ds_write_b16_d16_hi v46, v29 offset:12800
	v_mul_f32_e32 v29, v37, v18
	v_bfe_u32 v36, v29, 16, 1
	v_add3_u32 v29, v29, v36, s15
	v_add3_u32 v36, v38, v171, v27
	ds_write_b16_d16_hi v36, v29 offset:13056
	v_sub_f32_e32 v29, v34, v39
	v_mul_f32_e32 v29, v29, v18
	v_bfe_u32 v34, v29, 16, 1
	v_add3_u32 v29, v29, v34, s15
	v_add3_u32 v34, v38, v170, v27
	ds_write_b16_d16_hi v34, v29 offset:13312
	v_sub_f32_e32 v29, v24, v39
	v_pk_fma_f32 v[24:25], v[40:41], s[22:23], v[24:25] op_sel_hi:[1,0,1] neg_lo:[1,0,0] neg_hi:[1,0,0]
	v_mul_f32_e32 v29, v29, v18
	v_mul_f32_e32 v24, v25, v18
	v_bfe_u32 v34, v29, 16, 1
	v_bfe_u32 v25, v24, 16, 1
	v_add3_u32 v29, v29, v34, s15
	v_add3_u32 v34, v38, v169, v27
	v_add3_u32 v24, v24, v25, s15
	v_add3_u32 v25, v38, v167, v27
	ds_write_b16_d16_hi v34, v29 offset:13568
	ds_write_b16_d16_hi v25, v24 offset:13824
	v_pk_fma_f32 v[24:25], v[40:41], s[22:23], v[32:33] op_sel_hi:[1,0,1] neg_lo:[1,0,0] neg_hi:[1,0,0]
	v_and_b32_e32 v133, 15, v43
	v_mul_f32_e32 v24, v25, v18
	v_bfe_u32 v25, v24, 16, 1
	v_add3_u32 v24, v24, v25, s15
	v_add3_u32 v25, v38, v165, v27
	ds_write_b16_d16_hi v25, v24 offset:14080
	v_sub_f32_e32 v24, v28, v39
	v_mul_f32_e32 v24, v24, v18
	v_bfe_u32 v25, v24, 16, 1
	v_add3_u32 v24, v24, v25, s15
	ds_write_b16_d16_hi v35, v24 offset:14336
	v_sub_f32_e32 v24, v22, v39
	v_pk_fma_f32 v[22:23], v[40:41], s[22:23], v[22:23] op_sel_hi:[1,0,1] neg_lo:[1,0,0] neg_hi:[1,0,0]
	v_mul_f32_e32 v24, v24, v18
	v_mul_f32_e32 v22, v23, v18
	v_bfe_u32 v25, v24, 16, 1
	v_bfe_u32 v23, v22, 16, 1
	v_add3_u32 v24, v24, v25, s15
	v_add3_u32 v22, v22, v23, s15
	ds_write_b16_d16_hi v55, v24 offset:14592
	ds_write_b16_d16_hi v56, v22 offset:14848
	v_pk_fma_f32 v[22:23], v[40:41], s[22:23], v[30:31] op_sel_hi:[1,0,1] neg_lo:[1,0,0] neg_hi:[1,0,0]
	s_nop 0
	v_mul_f32_e32 v22, v23, v18
	v_bfe_u32 v23, v22, 16, 1
	v_add3_u32 v22, v22, v23, s15
	ds_write_b16_d16_hi v54, v22 offset:15104
	v_sub_f32_e32 v22, v26, v39
	v_mul_f32_e32 v22, v22, v18
	v_bfe_u32 v23, v22, 16, 1
	v_add3_u32 v22, v22, v23, s15
	ds_write_b16_d16_hi v53, v22 offset:15360
	v_sub_f32_e32 v22, v20, v39
	v_pk_fma_f32 v[20:21], v[40:41], s[22:23], v[20:21] op_sel_hi:[1,0,1] neg_lo:[1,0,0] neg_hi:[1,0,0]
	v_mul_f32_e32 v22, v22, v18
	v_mul_f32_e32 v20, v21, v18
	v_mul_f32_e32 v18, v19, v18
	v_bfe_u32 v23, v22, 16, 1
	v_bfe_u32 v21, v20, 16, 1
	v_bfe_u32 v19, v18, 16, 1
	v_add3_u32 v22, v22, v23, s15
	v_add3_u32 v20, v20, v21, s15
	v_add3_u32 v18, v18, v19, s15
	ds_write_b16_d16_hi v51, v22 offset:15616
	ds_write_b16_d16_hi v49, v20 offset:15872
	ds_write_b16_d16_hi v45, v18 offset:16128
	v_lshrrev_b32_e32 v18, 1, v43
	v_and_b32_e32 v18, 32, v18
	v_lshl_or_b32 v132, v44, 6, v18
	v_or_b32_e32 v18, v132, v134
	v_lshl_add_u32 v131, v18, 8, 32
	v_bitop3_b32 v18, v42, v133, 1 bitop3:0x6c
	v_lshl_add_u32 v18, v18, 4, v131
	s_waitcnt lgkmcnt(0)
	s_barrier
	ds_read_b128 v[136:139], v18 offset:55296
	s_waitcnt lgkmcnt(0)
	v_mfma_f32_32x32x16_bf16 v[50:65], v[136:139], v[2:5], 0
	v_mfma_f32_32x32x16_bf16 v[34:49], v[136:139], v[6:9], 0
	v_mfma_f32_32x32x16_bf16 v[18:33], v[136:139], v[10:13], 0
	v_mfma_f32_32x32x16_bf16 v[2:17], v[136:139], v[14:17], 0
	v_bitop3_b32 v136, v135, v133, 2 bitop3:0x36
	v_lshl_add_u32 v136, v136, 4, v131
	ds_read_b128 v[136:139], v136 offset:55296
	s_waitcnt lgkmcnt(0)
	v_mfma_f32_32x32x16_bf16 v[50:65], v[136:139], v[114:117], v[50:65]
	v_bitop3_b32 v114, v135, v133, 4 bitop3:0x36
	v_lshl_add_u32 v114, v114, 4, v131
	ds_read_b128 v[114:117], v114 offset:55296
	v_mfma_f32_32x32x16_bf16 v[34:49], v[136:139], v[118:121], v[34:49]
	v_mfma_f32_32x32x16_bf16 v[18:33], v[136:139], v[122:125], v[18:33]
	s_waitcnt lgkmcnt(0)
	v_mfma_f32_32x32x16_bf16 v[34:49], v[114:117], v[102:105], v[34:49]
	v_bitop3_b32 v102, v135, v133, 6 bitop3:0x36
	v_lshl_add_u32 v102, v102, 4, v131
	ds_read_b128 v[102:105], v102 offset:55296
	v_mfma_f32_32x32x16_bf16 v[2:17], v[136:139], v[126:129], v[2:17]
	v_mfma_f32_32x32x16_bf16 v[18:33], v[114:117], v[106:109], v[18:33]
	s_waitcnt lgkmcnt(0)
	v_mfma_f32_32x32x16_bf16 v[34:49], v[102:105], v[90:93], v[34:49]
	v_bitop3_b32 v90, v135, v133, 8 bitop3:0x36
	v_lshl_add_u32 v90, v90, 4, v131
	ds_read_b128 v[90:93], v90 offset:55296
	v_mfma_f32_32x32x16_bf16 v[2:17], v[114:117], v[110:113], v[2:17]
	v_mfma_f32_32x32x16_bf16 v[18:33], v[102:105], v[94:97], v[18:33]
	v_mfma_f32_32x32x16_bf16 v[2:17], v[102:105], v[98:101], v[2:17]
	v_lshlrev_b32_e32 v104, 7, v130
	v_or_b32_e32 v102, v104, v134
	v_ashrrev_i32_e32 v103, 31, v102
	v_lshlrev_b64 v[106:107], 2, v[102:103]
	v_lshl_or_b32 v98, v135, 2, v132
	v_or_b32_e32 v100, s3, v134
	v_mov_b32_e32 v101, s5
	s_waitcnt lgkmcnt(0)
	v_mfma_f32_32x32x16_bf16 v[18:33], v[90:93], v[82:85], v[18:33]
	v_bitop3_b32 v82, v135, v133, 10 bitop3:0x36
	v_lshl_add_u32 v82, v82, 4, v131
	ds_read_b128 v[82:85], v82 offset:55296
	v_lshl_add_u64 v[108:109], s[6:7], 0, v[106:107]
	v_lshl_add_u64 v[106:107], s[92:93], 0, v[106:107]
	v_ashrrev_i32_e32 v99, 31, v98
	v_lshlrev_b64 v[98:99], 1, v[98:99]
	v_mfma_f32_32x32x16_bf16 v[2:17], v[90:93], v[86:89], v[2:17]
	s_add_i32 s3, s3, s18
	s_cmpk_gt_i32 s4, 0x7f
	s_waitcnt lgkmcnt(0)
	v_mfma_f32_32x32x16_bf16 v[18:33], v[82:85], v[74:77], v[18:33]
	v_bitop3_b32 v74, v135, v133, 12 bitop3:0x36
	v_lshl_add_u32 v74, v74, 4, v131
	ds_read_b128 v[74:77], v74 offset:55296
	v_mfma_f32_32x32x16_bf16 v[2:17], v[82:85], v[78:81], v[2:17]
	s_waitcnt lgkmcnt(0)
	v_mfma_f32_32x32x16_bf16 v[2:17], v[74:77], v[70:73], v[2:17]
	v_bitop3_b32 v70, v135, v133, 14 bitop3:0x36
	v_lshl_add_u32 v70, v70, 4, v131
	ds_read_b128 v[70:73], v70 offset:55296
	v_ashrrev_i32_e32 v133, 31, v132
	s_waitcnt lgkmcnt(0)
	v_mfma_f32_32x32x16_bf16 v[2:17], v[70:73], v[66:69], v[2:17]
	v_lshlrev_b64 v[66:67], 2, v[132:133]
	v_lshl_add_u64 v[68:69], s[10:11], 0, v[66:67]
	v_lshl_add_u64 v[66:67], s[36:37], 0, v[66:67]
	v_lshl_add_u64 v[68:69], v[68:69], 0, v[154:155]
	v_lshl_add_u64 v[70:71], v[66:67], 0, v[154:155]
	global_load_dwordx4 v[90:93], v[68:69], off
	global_load_dwordx4 v[94:97], v[70:71], off
	global_load_dwordx4 v[82:85], v[68:69], off offset:32
	global_load_dwordx4 v[86:89], v[70:71], off offset:32
	global_load_dwordx4 v[74:77], v[68:69], off offset:64
	global_load_dwordx4 v[78:81], v[70:71], off offset:64
	s_nop 0
	global_load_dwordx4 v[66:69], v[68:69], off offset:96
	s_nop 0
	global_load_dwordx4 v[70:73], v[70:71], off offset:96
	s_nop 0
	global_load_dword v150, v[108:109], off
	global_load_dword v151, v[108:109], off offset:128
	global_load_dword v152, v[108:109], off offset:256
	global_load_dword v153, v[108:109], off offset:384
	global_load_dword v164, v[106:107], off
	global_load_dword v165, v[106:107], off offset:128
	global_load_dword v166, v[106:107], off offset:256
	global_load_dword v167, v[106:107], off offset:384
	v_lshlrev_b64 v[142:143], 11, v[100:101]
	v_lshl_add_u64 v[142:143], s[62:63], 0, v[142:143]
	v_lshl_add_u64 v[142:143], v[142:143], 0, v[98:99]
	v_add_co_u32_e32 v144, vcc, 0x10000, v142
	s_nop 1
	v_addc_co_u32_e32 v145, vcc, 0, v143, vcc
	v_add_co_u32_e32 v146, vcc, 0x20000, v142
	s_nop 1
	v_addc_co_u32_e32 v147, vcc, 0, v143, vcc
	v_add_co_u32_e32 v148, vcc, 0x30000, v142
	s_nop 1
	v_addc_co_u32_e32 v149, vcc, 0, v143, vcc
	s_waitcnt vmcnt(0)
	v_mul_f32_e32 v168, v94, v150
	v_fmac_f32_e32 v168, v50, v90
	v_add_f32_e32 v50, v164, v168
	v_lshlrev_b32_e32 v169, 16, v216
	v_mul_f32_e32 v50, v50, v169
	v_mul_f32_e32 v168, v95, v150
	v_fmac_f32_e32 v168, v51, v91
	v_add_f32_e32 v51, v164, v168
	v_and_b32_e32 v169, 0xffff0000, v216
	v_mul_f32_e32 v51, v51, v169
	v_mul_f32_e32 v168, v96, v150
	v_fmac_f32_e32 v168, v52, v92
	v_add_f32_e32 v52, v164, v168
	v_lshlrev_b32_e32 v169, 16, v217
	v_mul_f32_e32 v52, v52, v169
	v_mul_f32_e32 v168, v97, v150
	v_fmac_f32_e32 v168, v53, v93
	v_add_f32_e32 v53, v164, v168
	v_and_b32_e32 v169, 0xffff0000, v217
	v_mul_f32_e32 v53, v53, v169
	v_cvt_pk_bf16_f32 v50, v50, v51
	v_cvt_pk_bf16_f32 v51, v52, v53
	global_store_dwordx2 v[142:143], v[50:51], off offset:1536
	v_mul_f32_e32 v168, v86, v150
	v_fmac_f32_e32 v168, v54, v82
	v_add_f32_e32 v54, v164, v168
	v_lshlrev_b32_e32 v169, 16, v218
	v_mul_f32_e32 v54, v54, v169
	v_mul_f32_e32 v168, v87, v150
	v_fmac_f32_e32 v168, v55, v83
	v_add_f32_e32 v55, v164, v168
	v_and_b32_e32 v169, 0xffff0000, v218
	v_mul_f32_e32 v55, v55, v169
	v_mul_f32_e32 v168, v88, v150
	v_fmac_f32_e32 v168, v56, v84
	v_add_f32_e32 v56, v164, v168
	v_lshlrev_b32_e32 v169, 16, v219
	v_mul_f32_e32 v56, v56, v169
	v_mul_f32_e32 v168, v89, v150
	v_fmac_f32_e32 v168, v57, v85
	v_add_f32_e32 v57, v164, v168
	v_and_b32_e32 v169, 0xffff0000, v219
	v_mul_f32_e32 v57, v57, v169
	v_cvt_pk_bf16_f32 v54, v54, v55
	v_cvt_pk_bf16_f32 v55, v56, v57
	global_store_dwordx2 v[142:143], v[54:55], off offset:1552
	v_mul_f32_e32 v168, v78, v150
	v_fmac_f32_e32 v168, v58, v74
	v_add_f32_e32 v58, v164, v168
	v_lshlrev_b32_e32 v169, 16, v220
	v_mul_f32_e32 v58, v58, v169
	v_mul_f32_e32 v168, v79, v150
	v_fmac_f32_e32 v168, v59, v75
	v_add_f32_e32 v59, v164, v168
	v_and_b32_e32 v169, 0xffff0000, v220
	v_mul_f32_e32 v59, v59, v169
	v_mul_f32_e32 v168, v80, v150
	v_fmac_f32_e32 v168, v60, v76
	v_add_f32_e32 v60, v164, v168
	v_lshlrev_b32_e32 v169, 16, v221
	v_mul_f32_e32 v60, v60, v169
	v_mul_f32_e32 v168, v81, v150
	v_fmac_f32_e32 v168, v61, v77
	v_add_f32_e32 v61, v164, v168
	v_and_b32_e32 v169, 0xffff0000, v221
	v_mul_f32_e32 v61, v61, v169
	v_cvt_pk_bf16_f32 v58, v58, v59
	v_cvt_pk_bf16_f32 v59, v60, v61
	global_store_dwordx2 v[142:143], v[58:59], off offset:1568
	v_mul_f32_e32 v168, v70, v150
	v_fmac_f32_e32 v168, v62, v66
	v_add_f32_e32 v62, v164, v168
	v_lshlrev_b32_e32 v169, 16, v222
	v_mul_f32_e32 v62, v62, v169
	v_mul_f32_e32 v168, v71, v150
	v_fmac_f32_e32 v168, v63, v67
	v_add_f32_e32 v63, v164, v168
	v_and_b32_e32 v169, 0xffff0000, v222
	v_mul_f32_e32 v63, v63, v169
	v_mul_f32_e32 v168, v72, v150
	v_fmac_f32_e32 v168, v64, v68
	v_add_f32_e32 v64, v164, v168
	v_lshlrev_b32_e32 v169, 16, v223
	v_mul_f32_e32 v64, v64, v169
	v_mul_f32_e32 v168, v73, v150
	v_fmac_f32_e32 v168, v65, v69
	v_add_f32_e32 v65, v164, v168
	v_and_b32_e32 v169, 0xffff0000, v223
	v_mul_f32_e32 v65, v65, v169
	v_cvt_pk_bf16_f32 v62, v62, v63
	v_cvt_pk_bf16_f32 v63, v64, v65
	global_store_dwordx2 v[142:143], v[62:63], off offset:1584
	v_mul_f32_e32 v168, v94, v151
	v_fmac_f32_e32 v168, v34, v90
	v_add_f32_e32 v34, v165, v168
	v_lshlrev_b32_e32 v169, 16, v224
	v_mul_f32_e32 v34, v34, v169
	v_mul_f32_e32 v168, v95, v151
	v_fmac_f32_e32 v168, v35, v91
	v_add_f32_e32 v35, v165, v168
	v_and_b32_e32 v169, 0xffff0000, v224
	v_mul_f32_e32 v35, v35, v169
	v_mul_f32_e32 v168, v96, v151
	v_fmac_f32_e32 v168, v36, v92
	v_add_f32_e32 v36, v165, v168
	v_lshlrev_b32_e32 v169, 16, v225
	v_mul_f32_e32 v36, v36, v169
	v_mul_f32_e32 v168, v97, v151
	v_fmac_f32_e32 v168, v37, v93
	v_add_f32_e32 v37, v165, v168
	v_and_b32_e32 v169, 0xffff0000, v225
	v_mul_f32_e32 v37, v37, v169
	v_cvt_pk_bf16_f32 v34, v34, v35
	v_cvt_pk_bf16_f32 v35, v36, v37
	global_store_dwordx2 v[144:145], v[34:35], off offset:1536
	v_mul_f32_e32 v168, v86, v151
	v_fmac_f32_e32 v168, v38, v82
	v_add_f32_e32 v38, v165, v168
	v_lshlrev_b32_e32 v169, 16, v226
	v_mul_f32_e32 v38, v38, v169
	v_mul_f32_e32 v168, v87, v151
	v_fmac_f32_e32 v168, v39, v83
	v_add_f32_e32 v39, v165, v168
	v_and_b32_e32 v169, 0xffff0000, v226
	v_mul_f32_e32 v39, v39, v169
	v_mul_f32_e32 v168, v88, v151
	v_fmac_f32_e32 v168, v40, v84
	v_add_f32_e32 v40, v165, v168
	v_lshlrev_b32_e32 v169, 16, v227
	v_mul_f32_e32 v40, v40, v169
	v_mul_f32_e32 v168, v89, v151
	v_fmac_f32_e32 v168, v41, v85
	v_add_f32_e32 v41, v165, v168
	v_and_b32_e32 v169, 0xffff0000, v227
	v_mul_f32_e32 v41, v41, v169
	v_cvt_pk_bf16_f32 v38, v38, v39
	v_cvt_pk_bf16_f32 v39, v40, v41
	global_store_dwordx2 v[144:145], v[38:39], off offset:1552
	v_mul_f32_e32 v168, v78, v151
	v_fmac_f32_e32 v168, v42, v74
	v_add_f32_e32 v42, v165, v168
	v_lshlrev_b32_e32 v169, 16, v228
	v_mul_f32_e32 v42, v42, v169
	v_mul_f32_e32 v168, v79, v151
	v_fmac_f32_e32 v168, v43, v75
	v_add_f32_e32 v43, v165, v168
	v_and_b32_e32 v169, 0xffff0000, v228
	v_mul_f32_e32 v43, v43, v169
	v_mul_f32_e32 v168, v80, v151
	v_fmac_f32_e32 v168, v44, v76
	v_add_f32_e32 v44, v165, v168
	v_lshlrev_b32_e32 v169, 16, v229
	v_mul_f32_e32 v44, v44, v169
	v_mul_f32_e32 v168, v81, v151
	v_fmac_f32_e32 v168, v45, v77
	v_add_f32_e32 v45, v165, v168
	v_and_b32_e32 v169, 0xffff0000, v229
	v_mul_f32_e32 v45, v45, v169
	v_cvt_pk_bf16_f32 v42, v42, v43
	v_cvt_pk_bf16_f32 v43, v44, v45
	global_store_dwordx2 v[144:145], v[42:43], off offset:1568
	v_mul_f32_e32 v168, v70, v151
	v_fmac_f32_e32 v168, v46, v66
	v_add_f32_e32 v46, v165, v168
	v_lshlrev_b32_e32 v169, 16, v230
	v_mul_f32_e32 v46, v46, v169
	v_mul_f32_e32 v168, v71, v151
	v_fmac_f32_e32 v168, v47, v67
	v_add_f32_e32 v47, v165, v168
	v_and_b32_e32 v169, 0xffff0000, v230
	v_mul_f32_e32 v47, v47, v169
	v_mul_f32_e32 v168, v72, v151
	v_fmac_f32_e32 v168, v48, v68
	v_add_f32_e32 v48, v165, v168
	v_lshlrev_b32_e32 v169, 16, v231
	v_mul_f32_e32 v48, v48, v169
	v_mul_f32_e32 v168, v73, v151
	v_fmac_f32_e32 v168, v49, v69
	v_add_f32_e32 v49, v165, v168
	v_and_b32_e32 v169, 0xffff0000, v231
	v_mul_f32_e32 v49, v49, v169
	v_cvt_pk_bf16_f32 v46, v46, v47
	v_cvt_pk_bf16_f32 v47, v48, v49
	global_store_dwordx2 v[144:145], v[46:47], off offset:1584
	v_mul_f32_e32 v168, v94, v152
	v_fmac_f32_e32 v168, v18, v90
	v_add_f32_e32 v18, v166, v168
	v_lshlrev_b32_e32 v169, 16, v232
	v_mul_f32_e32 v18, v18, v169
	v_mul_f32_e32 v168, v95, v152
	v_fmac_f32_e32 v168, v19, v91
	v_add_f32_e32 v19, v166, v168
	v_and_b32_e32 v169, 0xffff0000, v232
	v_mul_f32_e32 v19, v19, v169
	v_mul_f32_e32 v168, v96, v152
	v_fmac_f32_e32 v168, v20, v92
	v_add_f32_e32 v20, v166, v168
	v_lshlrev_b32_e32 v169, 16, v233
	v_mul_f32_e32 v20, v20, v169
	v_mul_f32_e32 v168, v97, v152
	v_fmac_f32_e32 v168, v21, v93
	v_add_f32_e32 v21, v166, v168
	v_and_b32_e32 v169, 0xffff0000, v233
	v_mul_f32_e32 v21, v21, v169
	v_cvt_pk_bf16_f32 v18, v18, v19
	v_cvt_pk_bf16_f32 v19, v20, v21
	global_store_dwordx2 v[146:147], v[18:19], off offset:1536
	v_mul_f32_e32 v168, v86, v152
	v_fmac_f32_e32 v168, v22, v82
	v_add_f32_e32 v22, v166, v168
	v_lshlrev_b32_e32 v169, 16, v234
	v_mul_f32_e32 v22, v22, v169
	v_mul_f32_e32 v168, v87, v152
	v_fmac_f32_e32 v168, v23, v83
	v_add_f32_e32 v23, v166, v168
	v_and_b32_e32 v169, 0xffff0000, v234
	v_mul_f32_e32 v23, v23, v169
	v_mul_f32_e32 v168, v88, v152
	v_fmac_f32_e32 v168, v24, v84
	v_add_f32_e32 v24, v166, v168
	v_lshlrev_b32_e32 v169, 16, v235
	v_mul_f32_e32 v24, v24, v169
	v_mul_f32_e32 v168, v89, v152
	v_fmac_f32_e32 v168, v25, v85
	v_add_f32_e32 v25, v166, v168
	v_and_b32_e32 v169, 0xffff0000, v235
	v_mul_f32_e32 v25, v25, v169
	v_cvt_pk_bf16_f32 v22, v22, v23
	v_cvt_pk_bf16_f32 v23, v24, v25
	global_store_dwordx2 v[146:147], v[22:23], off offset:1552
	v_mul_f32_e32 v168, v78, v152
	v_fmac_f32_e32 v168, v26, v74
	v_add_f32_e32 v26, v166, v168
	v_lshlrev_b32_e32 v169, 16, v236
	v_mul_f32_e32 v26, v26, v169
	v_mul_f32_e32 v168, v79, v152
	v_fmac_f32_e32 v168, v27, v75
	v_add_f32_e32 v27, v166, v168
	v_and_b32_e32 v169, 0xffff0000, v236
	v_mul_f32_e32 v27, v27, v169
	v_mul_f32_e32 v168, v80, v152
	v_fmac_f32_e32 v168, v28, v76
	v_add_f32_e32 v28, v166, v168
	v_lshlrev_b32_e32 v169, 16, v237
	v_mul_f32_e32 v28, v28, v169
	v_mul_f32_e32 v168, v81, v152
	v_fmac_f32_e32 v168, v29, v77
	v_add_f32_e32 v29, v166, v168
	v_and_b32_e32 v169, 0xffff0000, v237
	v_mul_f32_e32 v29, v29, v169
	v_cvt_pk_bf16_f32 v26, v26, v27
	v_cvt_pk_bf16_f32 v27, v28, v29
	global_store_dwordx2 v[146:147], v[26:27], off offset:1568
	v_mul_f32_e32 v168, v70, v152
	v_fmac_f32_e32 v168, v30, v66
	v_add_f32_e32 v30, v166, v168
	v_lshlrev_b32_e32 v169, 16, v238
	v_mul_f32_e32 v30, v30, v169
	v_mul_f32_e32 v168, v71, v152
	v_fmac_f32_e32 v168, v31, v67
	v_add_f32_e32 v31, v166, v168
	v_and_b32_e32 v169, 0xffff0000, v238
	v_mul_f32_e32 v31, v31, v169
	v_mul_f32_e32 v168, v72, v152
	v_fmac_f32_e32 v168, v32, v68
	v_add_f32_e32 v32, v166, v168
	v_lshlrev_b32_e32 v169, 16, v239
	v_mul_f32_e32 v32, v32, v169
	v_mul_f32_e32 v168, v73, v152
	v_fmac_f32_e32 v168, v33, v69
	v_add_f32_e32 v33, v166, v168
	v_and_b32_e32 v169, 0xffff0000, v239
	v_mul_f32_e32 v33, v33, v169
	v_cvt_pk_bf16_f32 v30, v30, v31
	v_cvt_pk_bf16_f32 v31, v32, v33
	global_store_dwordx2 v[146:147], v[30:31], off offset:1584
	v_mul_f32_e32 v168, v94, v153
	v_fmac_f32_e32 v168, v2, v90
	v_add_f32_e32 v2, v167, v168
	v_lshlrev_b32_e32 v169, 16, v240
	v_mul_f32_e32 v2, v2, v169
	v_mul_f32_e32 v168, v95, v153
	v_fmac_f32_e32 v168, v3, v91
	v_add_f32_e32 v3, v167, v168
	v_and_b32_e32 v169, 0xffff0000, v240
	v_mul_f32_e32 v3, v3, v169
	v_mul_f32_e32 v168, v96, v153
	v_fmac_f32_e32 v168, v4, v92
	v_add_f32_e32 v4, v167, v168
	v_lshlrev_b32_e32 v169, 16, v241
	v_mul_f32_e32 v4, v4, v169
	v_mul_f32_e32 v168, v97, v153
	v_fmac_f32_e32 v168, v5, v93
	v_add_f32_e32 v5, v167, v168
	v_and_b32_e32 v169, 0xffff0000, v241
	v_mul_f32_e32 v5, v5, v169
	v_cvt_pk_bf16_f32 v2, v2, v3
	v_cvt_pk_bf16_f32 v3, v4, v5
	global_store_dwordx2 v[148:149], v[2:3], off offset:1536
	v_mul_f32_e32 v168, v86, v153
	v_fmac_f32_e32 v168, v6, v82
	v_add_f32_e32 v6, v167, v168
	v_lshlrev_b32_e32 v169, 16, v246
	v_mul_f32_e32 v6, v6, v169
	v_mul_f32_e32 v168, v87, v153
	v_fmac_f32_e32 v168, v7, v83
	v_add_f32_e32 v7, v167, v168
	v_and_b32_e32 v169, 0xffff0000, v246
	v_mul_f32_e32 v7, v7, v169
	v_mul_f32_e32 v168, v88, v153
	v_fmac_f32_e32 v168, v8, v84
	v_add_f32_e32 v8, v167, v168
	v_lshlrev_b32_e32 v169, 16, v247
	v_mul_f32_e32 v8, v8, v169
	v_mul_f32_e32 v168, v89, v153
	v_fmac_f32_e32 v168, v9, v85
	v_add_f32_e32 v9, v167, v168
	v_and_b32_e32 v169, 0xffff0000, v247
	v_mul_f32_e32 v9, v9, v169
	v_cvt_pk_bf16_f32 v6, v6, v7
	v_cvt_pk_bf16_f32 v7, v8, v9
	global_store_dwordx2 v[148:149], v[6:7], off offset:1552
	v_mul_f32_e32 v168, v78, v153
	v_fmac_f32_e32 v168, v10, v74
	v_add_f32_e32 v10, v167, v168
	v_lshlrev_b32_e32 v169, 16, v252
	v_mul_f32_e32 v10, v10, v169
	v_mul_f32_e32 v168, v79, v153
	v_fmac_f32_e32 v168, v11, v75
	v_add_f32_e32 v11, v167, v168
	v_and_b32_e32 v169, 0xffff0000, v252
	v_mul_f32_e32 v11, v11, v169
	v_mul_f32_e32 v168, v80, v153
	v_fmac_f32_e32 v168, v12, v76
	v_add_f32_e32 v12, v167, v168
	v_lshlrev_b32_e32 v169, 16, v253
	v_mul_f32_e32 v12, v12, v169
	v_mul_f32_e32 v168, v81, v153
	v_fmac_f32_e32 v168, v13, v77
	v_add_f32_e32 v13, v167, v168
	v_and_b32_e32 v169, 0xffff0000, v253
	v_mul_f32_e32 v13, v13, v169
	v_cvt_pk_bf16_f32 v10, v10, v11
	v_cvt_pk_bf16_f32 v11, v12, v13
	global_store_dwordx2 v[148:149], v[10:11], off offset:1568
	v_mul_f32_e32 v168, v70, v153
	v_fmac_f32_e32 v168, v14, v66
	v_add_f32_e32 v14, v167, v168
	v_lshlrev_b32_e32 v169, 16, v254
	v_mul_f32_e32 v14, v14, v169
	v_mul_f32_e32 v168, v71, v153
	v_fmac_f32_e32 v168, v15, v67
	v_add_f32_e32 v15, v167, v168
	v_and_b32_e32 v169, 0xffff0000, v254
	v_mul_f32_e32 v15, v15, v169
	v_mul_f32_e32 v168, v72, v153
	v_fmac_f32_e32 v168, v16, v68
	v_add_f32_e32 v16, v167, v168
	v_lshlrev_b32_e32 v169, 16, v255
	v_mul_f32_e32 v16, v16, v169
	v_mul_f32_e32 v168, v73, v153
	v_fmac_f32_e32 v168, v17, v69
	v_add_f32_e32 v17, v167, v168
	v_and_b32_e32 v169, 0xffff0000, v255
	v_mul_f32_e32 v17, v17, v169
	v_cvt_pk_bf16_f32 v14, v14, v15
	v_cvt_pk_bf16_f32 v15, v16, v17
	global_store_dwordx2 v[148:149], v[14:15], off offset:1584
	s_barrier
	s_cbranch_scc0 .LBB0_849
